# in-proj / out-proj / FF1 K-loops: 8 of the 16 LDS-DMA loads per iteration use scalar base + lane offset (no 64-bit VALU address add)
# speedup vs baseline: 1.0134x; 1.0019x over previous
; #define PG8_STAGE(bufoff, gbase, voff) do { _Pragma("unroll") for (int _i = 0; _i < 2; ++_i) \
;         __builtin_amdgcn_global_load_lds((const unsigned*)((const char*)(gbase) + (voff)[_i]), (LAS unsigned*)(lds + (bufoff) + ldsw + _i * 8192), 16, 0, 0); } while (0)
; #define PG8_LDA(dst, b, h) do { _Pragma("unroll") for (int m = 0; m < 4; ++m) _Pragma("unroll") for (int k = 0; k < 2; ++k) dst[m][k] = *(const LAS bf16x8*)(lds + PG8_SA(b, h) + aoff + m * 2048 + k * 1024); } while (0)
; #define PG8_LDB(dst, b, h) do { _Pragma("unroll") for (int n = 0; n < 2; ++n) _Pragma("unroll") for (int k = 0; k < 2; ++k) dst[n][k] = *(const LAS bf16x8*)(lds + PG8_SB(b, h) + boff + n * 2048 + k * 1024); } while (0)
; #define PG8_MMA(ai, bj, At, Bt) do { __builtin_amdgcn_s_setprio(1); _Pragma("unroll") for (int m = 0; m < 4; ++m) _Pragma("unroll") for (int n = 0; n < 2; ++n) _Pragma("unroll") for (int k = 0; k < 2; ++k) \
;         acc[ai][bj][m][n] = __builtin_amdgcn_mfma_f32_16x16x32_bf16(Bt[n][k], At[m][k], acc[ai][bj][m][n], 0, 0, 0); __builtin_amdgcn_s_setprio(0); } while (0)
; #define PG8_WAIT_V(n) asm volatile("s_waitcnt vmcnt(" #n ")" ::: "memory")
; #define PG8_WAIT_L(n) asm volatile("s_waitcnt lgkmcnt(" #n ")" ::: "memory")
; #define PG8_BAR __builtin_amdgcn_s_barrier()
; #define PG8_SCHED __builtin_amdgcn_sched_barrier(0)
; template <class Epi, class Sched>
; __device__ __forceinline__ void gemm_phase(LAS unsigned char* lds, const Gemm g, const Sched& S, const Epi& E) {
;     ...
;             PG8_LDB(B0, 0, 0); PG8_SCHED; PG8_LDA(At, 0, 0); PG8_STAGE(PG8_SA(1, 1), a1 + hstep, voffA);
;             PG8_WAIT_L(8); PG8_BAR; PG8_WAIT_L(0); PG8_MMA(0, 0, At, B0); PG8_BAR; PG8_SCHED;
;             PG8_LDB(B1, 0, 1); PG8_STAGE(PG8_SB(0, 0), b2, voffB);
;             PG8_BAR; PG8_WAIT_L(0); PG8_MMA(0, 1, At, B1); PG8_BAR;
;             PG8_LDA(At, 0, 1); PG8_STAGE(PG8_SA(0, 0), a2, voffA);
;             PG8_BAR; PG8_WAIT_L(0); PG8_MMA(1, 0, At, B0); PG8_BAR; PG8_SCHED;
;             PG8_STAGE(PG8_SB(0, 1), b2 + hstep, voffB);
;             PG8_WAIT_V(6); PG8_BAR; PG8_MMA(1, 1, At, B1); PG8_BAR;
.LBB0_342:
	s_nop 0
	v_add_u32_e32 v158, s42, v147
	ds_read_b128 v[142:145], v158
	ds_read_b128 v[150:153], v158 offset:1024
	ds_read_b128 v[154:157], v158 offset:2048
	ds_read_b128 v[158:161], v158 offset:3072
	s_add_u32 s18, s16, 0xfff80080
	s_addc_u32 s19, s17, -1
	s_cmp_eq_u32 s38, 28
	s_cselect_b32 s21, s11, s19
	s_cselect_b32 s20, s34, s18
	s_cselect_b32 s19, s9, s37
	s_cselect_b32 s18, s35, s36
	s_add_i32 m0, s24, 0xc000
	ds_read_b128 v[162:165], v149
	ds_read_b128 v[166:169], v149 offset:1024
	ds_read_b128 v[170:173], v149 offset:2048
	ds_read_b128 v[174:177], v149 offset:3072
	ds_read_b128 v[178:181], v149 offset:4096
	ds_read_b128 v[182:185], v149 offset:5120
	ds_read_b128 v[186:189], v149 offset:6144
	ds_read_b128 v[190:193], v149 offset:7168
	global_load_lds_dwordx4 v138, s[16:17]
	s_add_i32 m0, s24, 0xe000
	s_nop 0
	global_load_lds_dwordx4 v140, s[16:17]
	s_waitcnt lgkmcnt(8)
	s_barrier
	s_waitcnt lgkmcnt(0)
	v_mfma_f32_16x16x32_bf16 v[126:129], v[142:145], v[162:165], v[126:129]
	v_mfma_f32_16x16x32_bf16 v[122:125], v[154:157], v[162:165], v[122:125]
	v_mfma_f32_16x16x32_bf16 v[114:117], v[142:145], v[170:173], v[114:117]
	v_mfma_f32_16x16x32_bf16 v[106:109], v[154:157], v[170:173], v[106:109]
	v_mfma_f32_16x16x32_bf16 v[98:101], v[142:145], v[178:181], v[98:101]
	v_mfma_f32_16x16x32_bf16 v[90:93], v[154:157], v[178:181], v[90:93]
	v_mfma_f32_16x16x32_bf16 v[82:85], v[142:145], v[186:189], v[82:85]
	v_mfma_f32_16x16x32_bf16 v[74:77], v[154:157], v[186:189], v[74:77]
	v_mfma_f32_16x16x32_bf16 v[126:129], v[150:153], v[166:169], v[126:129]
	v_mfma_f32_16x16x32_bf16 v[122:125], v[158:161], v[166:169], v[122:125]
	v_mfma_f32_16x16x32_bf16 v[114:117], v[150:153], v[174:177], v[114:117]
	v_mfma_f32_16x16x32_bf16 v[106:109], v[158:161], v[174:177], v[106:109]
	v_mfma_f32_16x16x32_bf16 v[98:101], v[150:153], v[182:185], v[98:101]
	v_mfma_f32_16x16x32_bf16 v[90:93], v[158:161], v[182:185], v[90:93]
	v_mfma_f32_16x16x32_bf16 v[82:85], v[150:153], v[190:193], v[82:85]
	v_mfma_f32_16x16x32_bf16 v[74:77], v[158:161], v[190:193], v[74:77]
	s_barrier
	s_add_i32 s39, 0, 0x14000
	s_add_i32 s40, s42, s23
	v_add_u32_e32 v206, s39, v147
	v_lshl_add_u64 v[210:211], s[18:19], 0, v[0:1]
	s_mov_b32 m0, s40
	ds_read_b128 v[194:197], v206
	ds_read_b128 v[198:201], v206 offset:1024
	ds_read_b128 v[202:205], v206 offset:2048
	ds_read_b128 v[206:209], v206 offset:3072
	global_load_lds_dwordx4 v[210:211], off
	v_lshl_add_u64 v[220:221], s[18:19], 0, v[130:131]
	s_add_i32 m0, s40, 0x2000
	s_nop 0
	global_load_lds_dwordx4 v[220:221], off
	s_barrier
	s_waitcnt lgkmcnt(0)
	v_mfma_f32_16x16x32_bf16 v[118:121], v[194:197], v[162:165], v[118:121]
	v_mfma_f32_16x16x32_bf16 v[110:113], v[202:205], v[162:165], v[110:113]
	v_mfma_f32_16x16x32_bf16 v[102:105], v[194:197], v[170:173], v[102:105]
	v_mfma_f32_16x16x32_bf16 v[94:97], v[202:205], v[170:173], v[94:97]
	v_mfma_f32_16x16x32_bf16 v[86:89], v[194:197], v[178:181], v[86:89]
	v_mfma_f32_16x16x32_bf16 v[78:81], v[202:205], v[178:181], v[78:81]
	v_mfma_f32_16x16x32_bf16 v[70:73], v[194:197], v[186:189], v[70:73]
	v_mfma_f32_16x16x32_bf16 v[66:69], v[202:205], v[186:189], v[66:69]
	v_mfma_f32_16x16x32_bf16 v[118:121], v[198:201], v[166:169], v[118:121]
	v_mfma_f32_16x16x32_bf16 v[110:113], v[206:209], v[166:169], v[110:113]
	v_mfma_f32_16x16x32_bf16 v[102:105], v[198:201], v[174:177], v[102:105]
	v_mfma_f32_16x16x32_bf16 v[94:97], v[206:209], v[174:177], v[94:97]
	v_mfma_f32_16x16x32_bf16 v[86:89], v[198:201], v[182:185], v[86:89]
	v_mfma_f32_16x16x32_bf16 v[78:81], v[206:209], v[182:185], v[78:81]
	v_mfma_f32_16x16x32_bf16 v[70:73], v[198:201], v[190:193], v[70:73]
	v_mfma_f32_16x16x32_bf16 v[66:69], v[206:209], v[190:193], v[66:69]
	s_mov_b32 m0, s24
	v_lshl_add_u64 v[222:223], s[20:21], 0, v[134:135]
	s_barrier
	ds_read_b128 v[162:165], v149 offset:16384
	ds_read_b128 v[166:169], v149 offset:17408
	ds_read_b128 v[170:173], v149 offset:18432
	ds_read_b128 v[174:177], v149 offset:19456
	ds_read_b128 v[178:181], v149 offset:20480
	ds_read_b128 v[182:185], v149 offset:21504
	ds_read_b128 v[186:189], v149 offset:22528
	ds_read_b128 v[190:193], v149 offset:23552
	global_load_lds_dwordx4 v[222:223], off
	v_lshl_add_u64 v[234:235], s[20:21], 0, v[132:133]
	s_mov_b32 m0, s25
	s_nop 0
	global_load_lds_dwordx4 v[234:235], off
	s_barrier
	s_waitcnt lgkmcnt(0)
	v_mfma_f32_16x16x32_bf16 v[62:65], v[142:145], v[162:165], v[62:65]
	v_mfma_f32_16x16x32_bf16 v[58:61], v[154:157], v[162:165], v[58:61]
	v_mfma_f32_16x16x32_bf16 v[50:53], v[142:145], v[170:173], v[50:53]
	v_mfma_f32_16x16x32_bf16 v[42:45], v[154:157], v[170:173], v[42:45]
	v_mfma_f32_16x16x32_bf16 v[34:37], v[142:145], v[178:181], v[34:37]
	v_mfma_f32_16x16x32_bf16 v[26:29], v[154:157], v[178:181], v[26:29]
	v_mfma_f32_16x16x32_bf16 v[18:21], v[142:145], v[186:189], v[18:21]
	v_mfma_f32_16x16x32_bf16 v[10:13], v[154:157], v[186:189], v[10:13]
	v_mfma_f32_16x16x32_bf16 v[62:65], v[150:153], v[166:169], v[62:65]
	v_mfma_f32_16x16x32_bf16 v[58:61], v[158:161], v[166:169], v[58:61]
	v_mfma_f32_16x16x32_bf16 v[50:53], v[150:153], v[174:177], v[50:53]
	v_mfma_f32_16x16x32_bf16 v[42:45], v[158:161], v[174:177], v[42:45]
	v_mfma_f32_16x16x32_bf16 v[34:37], v[150:153], v[182:185], v[34:37]
	v_mfma_f32_16x16x32_bf16 v[26:29], v[158:161], v[182:185], v[26:29]
	v_mfma_f32_16x16x32_bf16 v[18:21], v[150:153], v[190:193], v[18:21]
	v_mfma_f32_16x16x32_bf16 v[10:13], v[158:161], v[190:193], v[10:13]
	s_barrier
	s_add_u32 s40, s18, 0x80000
	s_addc_u32 s41, s19, 0
	s_add_i32 s39, s39, s23
	s_mov_b32 m0, s39
	s_nop 0
	global_load_lds_dwordx4 v0, s[40:41]
	s_add_i32 m0, s39, 0x2000
	s_nop 0
	global_load_lds_dwordx4 v130, s[40:41]
	s_waitcnt vmcnt(6)
	s_barrier
; #define PG8_STAGE(bufoff, gbase, voff) do { _Pragma("unroll") for (int _i = 0; _i < 2; ++_i) \
;         __builtin_amdgcn_global_load_lds((const unsigned*)((const char*)(gbase) + (voff)[_i]), (LAS unsigned*)(lds + (bufoff) + ldsw + _i * 8192), 16, 0, 0); } while (0)
; #define PG8_LDA(dst, b, h) do { _Pragma("unroll") for (int m = 0; m < 4; ++m) _Pragma("unroll") for (int k = 0; k < 2; ++k) dst[m][k] = *(const LAS bf16x8*)(lds + PG8_SA(b, h) + aoff + m * 2048 + k * 1024); } while (0)
; #define PG8_LDB(dst, b, h) do { _Pragma("unroll") for (int n = 0; n < 2; ++n) _Pragma("unroll") for (int k = 0; k < 2; ++k) dst[n][k] = *(const LAS bf16x8*)(lds + PG8_SB(b, h) + boff + n * 2048 + k * 1024); } while (0)
; #define PG8_MMA(ai, bj, At, Bt) do { __builtin_amdgcn_s_setprio(1); _Pragma("unroll") for (int m = 0; m < 4; ++m) _Pragma("unroll") for (int n = 0; n < 2; ++n) _Pragma("unroll") for (int k = 0; k < 2; ++k) \
;         acc[ai][bj][m][n] = __builtin_amdgcn_mfma_f32_16x16x32_bf16(Bt[n][k], At[m][k], acc[ai][bj][m][n], 0, 0, 0); __builtin_amdgcn_s_setprio(0); } while (0)
; #define PG8_WAIT_V(n) asm volatile("s_waitcnt vmcnt(" #n ")" ::: "memory")
; #define PG8_WAIT_L(n) asm volatile("s_waitcnt lgkmcnt(" #n ")" ::: "memory")
; #define PG8_BAR __builtin_amdgcn_s_barrier()
; #define PG8_SCHED __builtin_amdgcn_sched_barrier(0)
; template <class Epi, class Sched>
; __device__ __forceinline__ void gemm_phase(LAS unsigned char* lds, const Gemm g, const Sched& S, const Epi& E) {
;     ...
;             PG8_STAGE(PG8_SB(0, 1), b2 + hstep, voffB);
;             PG8_WAIT_V(6); PG8_BAR; PG8_MMA(1, 1, At, B1); PG8_BAR;
;             PG8_LDB(B0, 1, 0); PG8_SCHED; PG8_LDA(At, 1, 0); PG8_STAGE(PG8_SA(0, 1), a2 + hstep, voffA);
;             PG8_WAIT_L(8); PG8_BAR; PG8_WAIT_L(0); PG8_MMA(0, 0, At, B0); PG8_BAR; PG8_SCHED;
;             PG8_LDB(B1, 1, 1); PG8_STAGE(PG8_SB(1, 0), b3, voffB);
;             PG8_BAR; PG8_WAIT_L(0); PG8_MMA(0, 1, At, B1); PG8_BAR;
;             PG8_LDA(At, 1, 1); PG8_STAGE(PG8_SA(1, 0), a3, voffA);
;             PG8_BAR; PG8_WAIT_L(0); PG8_MMA(1, 0, At, B0); PG8_BAR; PG8_SCHED;
	v_mfma_f32_16x16x32_bf16 v[54:57], v[194:197], v[162:165], v[54:57]
	v_mfma_f32_16x16x32_bf16 v[46:49], v[202:205], v[162:165], v[46:49]
	v_mfma_f32_16x16x32_bf16 v[38:41], v[194:197], v[170:173], v[38:41]
	v_mfma_f32_16x16x32_bf16 v[30:33], v[202:205], v[170:173], v[30:33]
	v_mfma_f32_16x16x32_bf16 v[22:25], v[194:197], v[178:181], v[22:25]
	v_mfma_f32_16x16x32_bf16 v[14:17], v[202:205], v[178:181], v[14:17]
	v_mfma_f32_16x16x32_bf16 v[6:9], v[194:197], v[186:189], v[6:9]
	v_mfma_f32_16x16x32_bf16 v[2:5], v[202:205], v[186:189], v[2:5]
	v_mfma_f32_16x16x32_bf16 v[54:57], v[198:201], v[166:169], v[54:57]
	v_mfma_f32_16x16x32_bf16 v[46:49], v[206:209], v[166:169], v[46:49]
	v_mfma_f32_16x16x32_bf16 v[38:41], v[198:201], v[174:177], v[38:41]
	v_mfma_f32_16x16x32_bf16 v[30:33], v[206:209], v[174:177], v[30:33]
	v_mfma_f32_16x16x32_bf16 v[22:25], v[198:201], v[182:185], v[22:25]
	v_mfma_f32_16x16x32_bf16 v[14:17], v[206:209], v[182:185], v[14:17]
	v_mfma_f32_16x16x32_bf16 v[6:9], v[198:201], v[190:193], v[6:9]
	v_mfma_f32_16x16x32_bf16 v[2:5], v[206:209], v[190:193], v[2:5]
	s_add_i32 s39, 0, 0x18000
	v_add_u32_e32 v158, s39, v147
	s_barrier
	ds_read_b128 v[142:145], v158
	ds_read_b128 v[150:153], v158 offset:1024
	ds_read_b128 v[154:157], v158 offset:2048
	ds_read_b128 v[158:161], v158 offset:3072
	s_add_u32 s20, s20, 0x80000
	s_addc_u32 s21, s21, 0
	s_mov_b32 m0, s26
	ds_read_b128 v[162:165], v149 offset:32768
	ds_read_b128 v[166:169], v149 offset:33792
	ds_read_b128 v[170:173], v149 offset:34816
	ds_read_b128 v[174:177], v149 offset:35840
	ds_read_b128 v[178:181], v149 offset:36864
	ds_read_b128 v[182:185], v149 offset:37888
	ds_read_b128 v[186:189], v149 offset:38912
	ds_read_b128 v[190:193], v149 offset:39936
	global_load_lds_dwordx4 v134, s[20:21]
	s_mov_b32 m0, s27
	s_nop 0
	global_load_lds_dwordx4 v132, s[20:21]
	s_waitcnt lgkmcnt(8)
	s_barrier
	s_waitcnt lgkmcnt(0)
	v_mfma_f32_16x16x32_bf16 v[126:129], v[142:145], v[162:165], v[126:129]
	v_mfma_f32_16x16x32_bf16 v[122:125], v[154:157], v[162:165], v[122:125]
	v_mfma_f32_16x16x32_bf16 v[114:117], v[142:145], v[170:173], v[114:117]
	v_mfma_f32_16x16x32_bf16 v[106:109], v[154:157], v[170:173], v[106:109]
	v_mfma_f32_16x16x32_bf16 v[98:101], v[142:145], v[178:181], v[98:101]
	v_mfma_f32_16x16x32_bf16 v[90:93], v[154:157], v[178:181], v[90:93]
	v_mfma_f32_16x16x32_bf16 v[82:85], v[142:145], v[186:189], v[82:85]
	v_mfma_f32_16x16x32_bf16 v[74:77], v[154:157], v[186:189], v[74:77]
	v_mfma_f32_16x16x32_bf16 v[126:129], v[150:153], v[166:169], v[126:129]
	v_mfma_f32_16x16x32_bf16 v[122:125], v[158:161], v[166:169], v[122:125]
	v_mfma_f32_16x16x32_bf16 v[114:117], v[150:153], v[174:177], v[114:117]
	v_mfma_f32_16x16x32_bf16 v[106:109], v[158:161], v[174:177], v[106:109]
	v_mfma_f32_16x16x32_bf16 v[98:101], v[150:153], v[182:185], v[98:101]
	v_mfma_f32_16x16x32_bf16 v[90:93], v[158:161], v[182:185], v[90:93]
	v_mfma_f32_16x16x32_bf16 v[82:85], v[150:153], v[190:193], v[82:85]
	v_mfma_f32_16x16x32_bf16 v[74:77], v[158:161], v[190:193], v[74:77]
	s_barrier
	s_add_i32 s20, 0, 0x1c000
	s_add_i32 s21, s39, s23
	v_add_u32_e32 v206, s20, v147
	v_lshl_add_u64 v[210:211], v[210:211], 0, s[44:45]
	s_mov_b32 m0, s21
	ds_read_b128 v[194:197], v206
	ds_read_b128 v[198:201], v206 offset:1024
	ds_read_b128 v[202:205], v206 offset:2048
	ds_read_b128 v[206:209], v206 offset:3072
	global_load_lds_dwordx4 v[210:211], off
	v_lshl_add_u64 v[210:211], v[220:221], 0, s[44:45]
	s_add_i32 m0, s21, 0x2000
	s_nop 0
	global_load_lds_dwordx4 v[210:211], off
	s_barrier
	s_waitcnt lgkmcnt(0)
	v_mfma_f32_16x16x32_bf16 v[118:121], v[194:197], v[162:165], v[118:121]
	v_mfma_f32_16x16x32_bf16 v[110:113], v[202:205], v[162:165], v[110:113]
	v_mfma_f32_16x16x32_bf16 v[102:105], v[194:197], v[170:173], v[102:105]
	v_mfma_f32_16x16x32_bf16 v[94:97], v[202:205], v[170:173], v[94:97]
	v_mfma_f32_16x16x32_bf16 v[86:89], v[194:197], v[178:181], v[86:89]
	v_mfma_f32_16x16x32_bf16 v[78:81], v[202:205], v[178:181], v[78:81]
	v_mfma_f32_16x16x32_bf16 v[70:73], v[194:197], v[186:189], v[70:73]
	v_mfma_f32_16x16x32_bf16 v[66:69], v[202:205], v[186:189], v[66:69]
	v_mfma_f32_16x16x32_bf16 v[118:121], v[198:201], v[166:169], v[118:121]
	v_mfma_f32_16x16x32_bf16 v[110:113], v[206:209], v[166:169], v[110:113]
	v_mfma_f32_16x16x32_bf16 v[102:105], v[198:201], v[174:177], v[102:105]
	v_mfma_f32_16x16x32_bf16 v[94:97], v[206:209], v[174:177], v[94:97]
	v_mfma_f32_16x16x32_bf16 v[86:89], v[198:201], v[182:185], v[86:89]
	v_mfma_f32_16x16x32_bf16 v[78:81], v[206:209], v[182:185], v[78:81]
	v_mfma_f32_16x16x32_bf16 v[70:73], v[198:201], v[190:193], v[70:73]
	v_mfma_f32_16x16x32_bf16 v[66:69], v[206:209], v[190:193], v[66:69]
	s_mov_b32 m0, s28
	v_lshl_add_u64 v[210:211], v[222:223], 0, s[44:45]
	s_barrier
; #define PG8_STAGE(bufoff, gbase, voff) do { _Pragma("unroll") for (int _i = 0; _i < 2; ++_i) \
;         __builtin_amdgcn_global_load_lds((const unsigned*)((const char*)(gbase) + (voff)[_i]), (LAS unsigned*)(lds + (bufoff) + ldsw + _i * 8192), 16, 0, 0); } while (0)
; #define PG8_LDA(dst, b, h) do { _Pragma("unroll") for (int m = 0; m < 4; ++m) _Pragma("unroll") for (int k = 0; k < 2; ++k) dst[m][k] = *(const LAS bf16x8*)(lds + PG8_SA(b, h) + aoff + m * 2048 + k * 1024); } while (0)
; #define PG8_MMA(ai, bj, At, Bt) do { __builtin_amdgcn_s_setprio(1); _Pragma("unroll") for (int m = 0; m < 4; ++m) _Pragma("unroll") for (int n = 0; n < 2; ++n) _Pragma("unroll") for (int k = 0; k < 2; ++k) \
;         acc[ai][bj][m][n] = __builtin_amdgcn_mfma_f32_16x16x32_bf16(Bt[n][k], At[m][k], acc[ai][bj][m][n], 0, 0, 0); __builtin_amdgcn_s_setprio(0); } while (0)
; #define PG8_WAIT_V(n) asm volatile("s_waitcnt vmcnt(" #n ")" ::: "memory")
; #define PG8_BAR __builtin_amdgcn_s_barrier()
; template <class Epi, class Sched>
; __device__ __forceinline__ void gemm_phase(LAS unsigned char* lds, const Gemm g, const Sched& S, const Epi& E) {
;     ...
;             PG8_LDA(At, 1, 1); PG8_STAGE(PG8_SA(1, 0), a3, voffA);
;             PG8_BAR; PG8_WAIT_L(0); PG8_MMA(1, 0, At, B0); PG8_BAR; PG8_SCHED;
;             PG8_STAGE(PG8_SB(1, 1), b3 + hstep, voffB);
;             PG8_WAIT_V(6); PG8_BAR; PG8_MMA(1, 1, At, B1); PG8_BAR;
;     __device__ __forceinline__ void operator()(const f32x4 (&acc)[2][2][4][2], const pg8::Unit& u, int wr, int wc, int fr, int fq) const {
;         const int row0 = u.pm * 256 + wr * 64 + fr; const int col0 = u.pn * 256 + wc * 32 + 8 * fq;
; #pragma unroll
;         for (int ai = 0; ai < 2; ++ai)
; #pragma unroll
;             for (int m = 0; m < 4; ++m) { const int row = row0 + ai * 128 + m * 16; bf16_t* rowp = O + (size_t)row * ldc + col0;
; #pragma unroll
;                 for (int bj = 0; bj < 2; ++bj) { f32x4 v0 = acc[ai][bj][m][0], v1 = acc[ai][bj][m][1];
;                     if (ACT == 1) {
; #pragma unroll
;                         for (int j = 0; j < 4; ++j) { float a = fmaxf(v0[j], 0.f), b = fmaxf(v1[j], 0.f); v0[j] = a * a; v1[j] = b * b; } }
;                     if (ACT == 0) { if (u.pn == (C_G / 256) && bj == 0 && wc == 0 && fq < 2) { float* gp = gate + (size_t)row * 16 + 8 * fq; *(f32x4*)gp = v0; *(f32x4*)(gp + 4) = v1; } }
	ds_read_b128 v[162:165], v149 offset:49152
	ds_read_b128 v[166:169], v149 offset:50176
	ds_read_b128 v[170:173], v149 offset:51200
	ds_read_b128 v[174:177], v149 offset:52224
	ds_read_b128 v[178:181], v149 offset:53248
	ds_read_b128 v[182:185], v149 offset:54272
	ds_read_b128 v[186:189], v149 offset:55296
	ds_read_b128 v[190:193], v149 offset:56320
	global_load_lds_dwordx4 v[210:211], off
	v_lshl_add_u64 v[210:211], v[234:235], 0, s[44:45]
	s_mov_b32 m0, s29
	s_nop 0
	global_load_lds_dwordx4 v[210:211], off
	s_barrier
	s_waitcnt lgkmcnt(0)
	v_mfma_f32_16x16x32_bf16 v[62:65], v[142:145], v[162:165], v[62:65]
	v_mfma_f32_16x16x32_bf16 v[58:61], v[154:157], v[162:165], v[58:61]
	v_mfma_f32_16x16x32_bf16 v[50:53], v[142:145], v[170:173], v[50:53]
	v_mfma_f32_16x16x32_bf16 v[42:45], v[154:157], v[170:173], v[42:45]
	v_mfma_f32_16x16x32_bf16 v[34:37], v[142:145], v[178:181], v[34:37]
	v_mfma_f32_16x16x32_bf16 v[26:29], v[154:157], v[178:181], v[26:29]
	v_mfma_f32_16x16x32_bf16 v[18:21], v[142:145], v[186:189], v[18:21]
	v_mfma_f32_16x16x32_bf16 v[10:13], v[154:157], v[186:189], v[10:13]
	v_mfma_f32_16x16x32_bf16 v[62:65], v[150:153], v[166:169], v[62:65]
	v_mfma_f32_16x16x32_bf16 v[58:61], v[158:161], v[166:169], v[58:61]
	v_mfma_f32_16x16x32_bf16 v[50:53], v[150:153], v[174:177], v[50:53]
	v_mfma_f32_16x16x32_bf16 v[42:45], v[158:161], v[174:177], v[42:45]
	v_mfma_f32_16x16x32_bf16 v[34:37], v[150:153], v[182:185], v[34:37]
	v_mfma_f32_16x16x32_bf16 v[26:29], v[158:161], v[182:185], v[26:29]
	v_mfma_f32_16x16x32_bf16 v[18:21], v[150:153], v[190:193], v[18:21]
	v_mfma_f32_16x16x32_bf16 v[10:13], v[158:161], v[190:193], v[10:13]
	s_barrier
	s_add_u32 s18, s18, 0x80080
	s_addc_u32 s19, s19, 0
	s_add_i32 s20, s20, s23
	s_mov_b32 m0, s20
	s_nop 0
	global_load_lds_dwordx4 v0, s[18:19]
	s_add_i32 m0, s20, 0x2000
	s_nop 0
	global_load_lds_dwordx4 v130, s[18:19]
	s_waitcnt vmcnt(6)
	s_barrier
	v_mfma_f32_16x16x32_bf16 v[54:57], v[194:197], v[162:165], v[54:57]
	v_mfma_f32_16x16x32_bf16 v[46:49], v[202:205], v[162:165], v[46:49]
	v_mfma_f32_16x16x32_bf16 v[38:41], v[194:197], v[170:173], v[38:41]
	v_mfma_f32_16x16x32_bf16 v[30:33], v[202:205], v[170:173], v[30:33]
	v_mfma_f32_16x16x32_bf16 v[22:25], v[194:197], v[178:181], v[22:25]
	v_mfma_f32_16x16x32_bf16 v[14:17], v[202:205], v[178:181], v[14:17]
	v_mfma_f32_16x16x32_bf16 v[6:9], v[194:197], v[186:189], v[6:9]
	v_mfma_f32_16x16x32_bf16 v[2:5], v[202:205], v[186:189], v[2:5]
	v_mfma_f32_16x16x32_bf16 v[54:57], v[198:201], v[166:169], v[54:57]
	v_mfma_f32_16x16x32_bf16 v[46:49], v[206:209], v[166:169], v[46:49]
	v_mfma_f32_16x16x32_bf16 v[38:41], v[198:201], v[174:177], v[38:41]
	v_mfma_f32_16x16x32_bf16 v[30:33], v[206:209], v[174:177], v[30:33]
	v_mfma_f32_16x16x32_bf16 v[22:25], v[198:201], v[182:185], v[22:25]
	v_mfma_f32_16x16x32_bf16 v[14:17], v[206:209], v[182:185], v[14:17]
	v_mfma_f32_16x16x32_bf16 v[6:9], v[198:201], v[190:193], v[6:9]
	v_mfma_f32_16x16x32_bf16 v[2:5], v[206:209], v[190:193], v[2:5]
	s_add_i32 s38, s38, 2
	s_add_u32 s16, s16, 0x100
	s_addc_u32 s17, s17, 0
	s_add_u32 s36, s36, 0x100
	s_addc_u32 s37, s37, 0
	s_cmp_gt_u32 s38, 29
	s_barrier
	s_cbranch_scc0 .LBB0_342
	s_cmp_eq_u32 s3, 18
	s_cselect_b64 s[16:17], -1, 0
	v_lshl_add_u32 v142, s31, 8, v146
	s_and_b64 s[16:17], s[6:7], s[16:17]
	v_ashrrev_i32_e32 v143, 31, v142
	s_and_b64 s[16:17], s[16:17], s[0:1]
	s_and_saveexec_b64 s[18:19], s[16:17]
	s_cbranch_execz .LBB0_345
	v_lshlrev_b64 v[144:145], 6, v[142:143]
	v_lshl_add_u64 v[144:145], v[136:137], 0, v[144:145]
	global_store_dwordx4 v[144:145], v[126:129], off
	global_store_dwordx4 v[144:145], v[122:125], off offset:16

; #define PG8_STAGE(bufoff, gbase, voff) do { _Pragma("unroll") for (int _i = 0; _i < 2; ++_i) \
;         __builtin_amdgcn_global_load_lds((const unsigned*)((const char*)(gbase) + (voff)[_i]), (LAS unsigned*)(lds + (bufoff) + ldsw + _i * 8192), 16, 0, 0); } while (0)
; #define PG8_LDA(dst, b, h) do { _Pragma("unroll") for (int m = 0; m < 4; ++m) _Pragma("unroll") for (int k = 0; k < 2; ++k) dst[m][k] = *(const LAS bf16x8*)(lds + PG8_SA(b, h) + aoff + m * 2048 + k * 1024); } while (0)
; #define PG8_LDB(dst, b, h) do { _Pragma("unroll") for (int n = 0; n < 2; ++n) _Pragma("unroll") for (int k = 0; k < 2; ++k) dst[n][k] = *(const LAS bf16x8*)(lds + PG8_SB(b, h) + boff + n * 2048 + k * 1024); } while (0)
; #define PG8_MMA(ai, bj, At, Bt) do { __builtin_amdgcn_s_setprio(1); _Pragma("unroll") for (int m = 0; m < 4; ++m) _Pragma("unroll") for (int n = 0; n < 2; ++n) _Pragma("unroll") for (int k = 0; k < 2; ++k) \
;         acc[ai][bj][m][n] = __builtin_amdgcn_mfma_f32_16x16x32_bf16(Bt[n][k], At[m][k], acc[ai][bj][m][n], 0, 0, 0); __builtin_amdgcn_s_setprio(0); } while (0)
; #define PG8_WAIT_V(n) asm volatile("s_waitcnt vmcnt(" #n ")" ::: "memory")
; #define PG8_WAIT_L(n) asm volatile("s_waitcnt lgkmcnt(" #n ")" ::: "memory")
; #define PG8_BAR __builtin_amdgcn_s_barrier()
; #define PG8_SCHED __builtin_amdgcn_sched_barrier(0)
; template <class Epi, class Sched>
; __device__ __forceinline__ void gemm_phase(LAS unsigned char* lds, const Gemm g, const Sched& S, const Epi& E) {
;     ...
;             PG8_LDB(B0, 0, 0); PG8_SCHED; PG8_LDA(At, 0, 0); PG8_STAGE(PG8_SA(1, 1), a1 + hstep, voffA);
;             PG8_WAIT_L(8); PG8_BAR; PG8_WAIT_L(0); PG8_MMA(0, 0, At, B0); PG8_BAR; PG8_SCHED;
;             PG8_LDB(B1, 0, 1); PG8_STAGE(PG8_SB(0, 0), b2, voffB);
;             PG8_BAR; PG8_WAIT_L(0); PG8_MMA(0, 1, At, B1); PG8_BAR;
;             PG8_LDA(At, 0, 1); PG8_STAGE(PG8_SA(0, 0), a2, voffA);
;             PG8_BAR; PG8_WAIT_L(0); PG8_MMA(1, 0, At, B0); PG8_BAR; PG8_SCHED;
;             PG8_STAGE(PG8_SB(0, 1), b2 + hstep, voffB);
;             PG8_WAIT_V(6); PG8_BAR; PG8_MMA(1, 1, At, B1); PG8_BAR;
.LBB0_1123:
	s_nop 0
	v_add_u32_e32 v0, s44, v151
	ds_read_b128 v[138:141], v0
	ds_read_b128 v[142:145], v0 offset:1024
	ds_read_b128 v[146:149], v0 offset:2048
	ds_read_b128 v[154:157], v0 offset:3072
	s_add_u32 s20, s18, 0x100
	s_addc_u32 s21, s19, 0
	s_cmp_eq_u32 s42, 28
	s_cselect_b32 s25, s3, s21
	s_cselect_b32 s24, s9, s20
	s_cselect_b32 s23, s1, s41
	s_cselect_b32 s22, s15, s17
	s_add_i32 m0, s31, 0xc000
	ds_read_b128 v[158:161], v153
	ds_read_b128 v[162:165], v153 offset:1024
	ds_read_b128 v[166:169], v153 offset:2048
	ds_read_b128 v[170:173], v153 offset:3072
	ds_read_b128 v[174:177], v153 offset:4096
	ds_read_b128 v[178:181], v153 offset:5120
	ds_read_b128 v[182:185], v153 offset:6144
	ds_read_b128 v[186:189], v153 offset:7168
	global_load_lds_dwordx4 v134, s[18:19]
	s_add_i32 m0, s31, 0xe000
	s_nop 0
	global_load_lds_dwordx4 v136, s[18:19]
	s_waitcnt lgkmcnt(8)
	s_barrier
	s_waitcnt lgkmcnt(0)
	v_mfma_f32_16x16x32_bf16 v[126:129], v[138:141], v[158:161], v[126:129]
	v_mfma_f32_16x16x32_bf16 v[122:125], v[146:149], v[158:161], v[122:125]
	v_mfma_f32_16x16x32_bf16 v[110:113], v[138:141], v[166:169], v[110:113]
	v_mfma_f32_16x16x32_bf16 v[106:109], v[146:149], v[166:169], v[106:109]
	v_mfma_f32_16x16x32_bf16 v[94:97], v[138:141], v[174:177], v[94:97]
	v_mfma_f32_16x16x32_bf16 v[90:93], v[146:149], v[174:177], v[90:93]
	v_mfma_f32_16x16x32_bf16 v[78:81], v[138:141], v[182:185], v[78:81]
	v_mfma_f32_16x16x32_bf16 v[74:77], v[146:149], v[182:185], v[74:77]
	v_mfma_f32_16x16x32_bf16 v[126:129], v[142:145], v[162:165], v[126:129]
	v_mfma_f32_16x16x32_bf16 v[122:125], v[154:157], v[162:165], v[122:125]
	v_mfma_f32_16x16x32_bf16 v[110:113], v[142:145], v[170:173], v[110:113]
	v_mfma_f32_16x16x32_bf16 v[106:109], v[154:157], v[170:173], v[106:109]
	v_mfma_f32_16x16x32_bf16 v[94:97], v[142:145], v[178:181], v[94:97]
	v_mfma_f32_16x16x32_bf16 v[90:93], v[154:157], v[178:181], v[90:93]
	v_mfma_f32_16x16x32_bf16 v[78:81], v[142:145], v[186:189], v[78:81]
	v_mfma_f32_16x16x32_bf16 v[74:77], v[154:157], v[186:189], v[74:77]
	s_barrier
	s_add_i32 s43, 0, 0x14000
	s_add_i32 s18, s44, s30
	v_add_u32_e32 v0, s43, v151
	v_lshl_add_u64 v[206:207], s[22:23], 0, v[130:131]
	s_mov_b32 m0, s18
	ds_read_b128 v[190:193], v0
	ds_read_b128 v[194:197], v0 offset:1024
	ds_read_b128 v[198:201], v0 offset:2048
	ds_read_b128 v[202:205], v0 offset:3072
	global_load_lds_dwordx4 v[206:207], off
	v_lshl_add_u64 v[208:209], s[22:23], 0, v[132:133]
	s_add_i32 m0, s18, 0x2000
	s_nop 0
	global_load_lds_dwordx4 v[208:209], off
	s_barrier
	s_waitcnt lgkmcnt(0)
	v_mfma_f32_16x16x32_bf16 v[118:121], v[190:193], v[158:161], v[118:121]
	v_mfma_f32_16x16x32_bf16 v[114:117], v[198:201], v[158:161], v[114:117]
	v_mfma_f32_16x16x32_bf16 v[102:105], v[190:193], v[166:169], v[102:105]
	v_mfma_f32_16x16x32_bf16 v[98:101], v[198:201], v[166:169], v[98:101]
	v_mfma_f32_16x16x32_bf16 v[86:89], v[190:193], v[174:177], v[86:89]
	v_mfma_f32_16x16x32_bf16 v[82:85], v[198:201], v[174:177], v[82:85]
	v_mfma_f32_16x16x32_bf16 v[70:73], v[190:193], v[182:185], v[70:73]
	v_mfma_f32_16x16x32_bf16 v[66:69], v[198:201], v[182:185], v[66:69]
	v_mfma_f32_16x16x32_bf16 v[118:121], v[194:197], v[162:165], v[118:121]
	v_mfma_f32_16x16x32_bf16 v[114:117], v[202:205], v[162:165], v[114:117]
	v_mfma_f32_16x16x32_bf16 v[102:105], v[194:197], v[170:173], v[102:105]
	v_mfma_f32_16x16x32_bf16 v[98:101], v[202:205], v[170:173], v[98:101]
	v_mfma_f32_16x16x32_bf16 v[86:89], v[194:197], v[178:181], v[86:89]
	v_mfma_f32_16x16x32_bf16 v[82:85], v[202:205], v[178:181], v[82:85]
	v_mfma_f32_16x16x32_bf16 v[70:73], v[194:197], v[186:189], v[70:73]
	v_mfma_f32_16x16x32_bf16 v[66:69], v[202:205], v[186:189], v[66:69]
	s_mov_b32 m0, s31
	v_lshl_add_u64 v[210:211], s[24:25], 0, v[130:131]
	s_barrier
	ds_read_b128 v[158:161], v153 offset:16384
	ds_read_b128 v[162:165], v153 offset:17408
	ds_read_b128 v[166:169], v153 offset:18432
	ds_read_b128 v[170:173], v153 offset:19456
	ds_read_b128 v[174:177], v153 offset:20480
	ds_read_b128 v[178:181], v153 offset:21504
	ds_read_b128 v[182:185], v153 offset:22528
	ds_read_b128 v[186:189], v153 offset:23552
	global_load_lds_dwordx4 v[210:211], off
	v_lshl_add_u64 v[220:221], s[24:25], 0, v[132:133]
	s_mov_b32 m0, s34
	s_nop 0
	global_load_lds_dwordx4 v[220:221], off
	s_barrier
	s_waitcnt lgkmcnt(0)
	v_mfma_f32_16x16x32_bf16 v[62:65], v[138:141], v[158:161], v[62:65]
	v_mfma_f32_16x16x32_bf16 v[58:61], v[146:149], v[158:161], v[58:61]
	v_mfma_f32_16x16x32_bf16 v[46:49], v[138:141], v[166:169], v[46:49]
	v_mfma_f32_16x16x32_bf16 v[42:45], v[146:149], v[166:169], v[42:45]
	v_mfma_f32_16x16x32_bf16 v[30:33], v[138:141], v[174:177], v[30:33]
	v_mfma_f32_16x16x32_bf16 v[26:29], v[146:149], v[174:177], v[26:29]
	v_mfma_f32_16x16x32_bf16 v[14:17], v[138:141], v[182:185], v[14:17]
	v_mfma_f32_16x16x32_bf16 v[10:13], v[146:149], v[182:185], v[10:13]
	v_mfma_f32_16x16x32_bf16 v[62:65], v[142:145], v[162:165], v[62:65]
	v_mfma_f32_16x16x32_bf16 v[58:61], v[154:157], v[162:165], v[58:61]
	v_mfma_f32_16x16x32_bf16 v[46:49], v[142:145], v[170:173], v[46:49]
	v_mfma_f32_16x16x32_bf16 v[42:45], v[154:157], v[170:173], v[42:45]
	v_mfma_f32_16x16x32_bf16 v[30:33], v[142:145], v[178:181], v[30:33]
	v_mfma_f32_16x16x32_bf16 v[26:29], v[154:157], v[178:181], v[26:29]
	v_mfma_f32_16x16x32_bf16 v[14:17], v[142:145], v[186:189], v[14:17]
	v_mfma_f32_16x16x32_bf16 v[10:13], v[154:157], v[186:189], v[10:13]
	s_barrier
	s_add_u32 s18, s22, 0x80000
	s_addc_u32 s19, s23, 0
	s_add_i32 s43, s43, s30
	s_mov_b32 m0, s43
	s_nop 0
	global_load_lds_dwordx4 v130, s[18:19]
	s_add_i32 m0, s43, 0x2000
	s_nop 0
	global_load_lds_dwordx4 v132, s[18:19]
	s_waitcnt vmcnt(6)
	s_barrier
; #define PG8_STAGE(bufoff, gbase, voff) do { _Pragma("unroll") for (int _i = 0; _i < 2; ++_i) \
;         __builtin_amdgcn_global_load_lds((const unsigned*)((const char*)(gbase) + (voff)[_i]), (LAS unsigned*)(lds + (bufoff) + ldsw + _i * 8192), 16, 0, 0); } while (0)
; #define PG8_LDA(dst, b, h) do { _Pragma("unroll") for (int m = 0; m < 4; ++m) _Pragma("unroll") for (int k = 0; k < 2; ++k) dst[m][k] = *(const LAS bf16x8*)(lds + PG8_SA(b, h) + aoff + m * 2048 + k * 1024); } while (0)
; #define PG8_LDB(dst, b, h) do { _Pragma("unroll") for (int n = 0; n < 2; ++n) _Pragma("unroll") for (int k = 0; k < 2; ++k) dst[n][k] = *(const LAS bf16x8*)(lds + PG8_SB(b, h) + boff + n * 2048 + k * 1024); } while (0)
; #define PG8_MMA(ai, bj, At, Bt) do { __builtin_amdgcn_s_setprio(1); _Pragma("unroll") for (int m = 0; m < 4; ++m) _Pragma("unroll") for (int n = 0; n < 2; ++n) _Pragma("unroll") for (int k = 0; k < 2; ++k) \
;         acc[ai][bj][m][n] = __builtin_amdgcn_mfma_f32_16x16x32_bf16(Bt[n][k], At[m][k], acc[ai][bj][m][n], 0, 0, 0); __builtin_amdgcn_s_setprio(0); } while (0)
; #define PG8_WAIT_V(n) asm volatile("s_waitcnt vmcnt(" #n ")" ::: "memory")
; #define PG8_WAIT_L(n) asm volatile("s_waitcnt lgkmcnt(" #n ")" ::: "memory")
; #define PG8_BAR __builtin_amdgcn_s_barrier()
; #define PG8_SCHED __builtin_amdgcn_sched_barrier(0)
; template <class Epi, class Sched>
; __device__ __forceinline__ void gemm_phase(LAS unsigned char* lds, const Gemm g, const Sched& S, const Epi& E) {
;     ...
;             PG8_STAGE(PG8_SB(0, 1), b2 + hstep, voffB);
;             PG8_WAIT_V(6); PG8_BAR; PG8_MMA(1, 1, At, B1); PG8_BAR;
;             PG8_LDB(B0, 1, 0); PG8_SCHED; PG8_LDA(At, 1, 0); PG8_STAGE(PG8_SA(0, 1), a2 + hstep, voffA);
;             PG8_WAIT_L(8); PG8_BAR; PG8_WAIT_L(0); PG8_MMA(0, 0, At, B0); PG8_BAR; PG8_SCHED;
;             PG8_LDB(B1, 1, 1); PG8_STAGE(PG8_SB(1, 0), b3, voffB);
;             PG8_BAR; PG8_WAIT_L(0); PG8_MMA(0, 1, At, B1); PG8_BAR;
;             PG8_LDA(At, 1, 1); PG8_STAGE(PG8_SA(1, 0), a3, voffA);
;             PG8_BAR; PG8_WAIT_L(0); PG8_MMA(1, 0, At, B0); PG8_BAR; PG8_SCHED;
	v_mfma_f32_16x16x32_bf16 v[54:57], v[190:193], v[158:161], v[54:57]
	v_mfma_f32_16x16x32_bf16 v[50:53], v[198:201], v[158:161], v[50:53]
	v_mfma_f32_16x16x32_bf16 v[38:41], v[190:193], v[166:169], v[38:41]
	v_mfma_f32_16x16x32_bf16 v[34:37], v[198:201], v[166:169], v[34:37]
	v_mfma_f32_16x16x32_bf16 v[22:25], v[190:193], v[174:177], v[22:25]
	v_mfma_f32_16x16x32_bf16 v[18:21], v[198:201], v[174:177], v[18:21]
	v_mfma_f32_16x16x32_bf16 v[6:9], v[190:193], v[182:185], v[6:9]
	v_mfma_f32_16x16x32_bf16 v[2:5], v[198:201], v[182:185], v[2:5]
	v_mfma_f32_16x16x32_bf16 v[54:57], v[194:197], v[162:165], v[54:57]
	v_mfma_f32_16x16x32_bf16 v[50:53], v[202:205], v[162:165], v[50:53]
	v_mfma_f32_16x16x32_bf16 v[38:41], v[194:197], v[170:173], v[38:41]
	v_mfma_f32_16x16x32_bf16 v[34:37], v[202:205], v[170:173], v[34:37]
	v_mfma_f32_16x16x32_bf16 v[22:25], v[194:197], v[178:181], v[22:25]
	v_mfma_f32_16x16x32_bf16 v[18:21], v[202:205], v[178:181], v[18:21]
	v_mfma_f32_16x16x32_bf16 v[6:9], v[194:197], v[186:189], v[6:9]
	v_mfma_f32_16x16x32_bf16 v[2:5], v[202:205], v[186:189], v[2:5]
	s_add_i32 s43, 0, 0x18000
	v_add_u32_e32 v0, s43, v151
	s_barrier
	ds_read_b128 v[138:141], v0
	ds_read_b128 v[142:145], v0 offset:1024
	ds_read_b128 v[146:149], v0 offset:2048
	ds_read_b128 v[154:157], v0 offset:3072
	s_add_u32 s18, s24, 0x80000
	s_addc_u32 s19, s25, 0
	s_mov_b32 m0, s35
	ds_read_b128 v[158:161], v153 offset:32768
	ds_read_b128 v[162:165], v153 offset:33792
	ds_read_b128 v[166:169], v153 offset:34816
	ds_read_b128 v[170:173], v153 offset:35840
	ds_read_b128 v[174:177], v153 offset:36864
	ds_read_b128 v[178:181], v153 offset:37888
	ds_read_b128 v[182:185], v153 offset:38912
	ds_read_b128 v[186:189], v153 offset:39936
	global_load_lds_dwordx4 v130, s[18:19]
	s_mov_b32 m0, s36
	s_nop 0
	global_load_lds_dwordx4 v132, s[18:19]
	s_waitcnt lgkmcnt(8)
	s_barrier
	s_waitcnt lgkmcnt(0)
	v_mfma_f32_16x16x32_bf16 v[126:129], v[138:141], v[158:161], v[126:129]
	v_mfma_f32_16x16x32_bf16 v[122:125], v[146:149], v[158:161], v[122:125]
	v_mfma_f32_16x16x32_bf16 v[110:113], v[138:141], v[166:169], v[110:113]
	v_mfma_f32_16x16x32_bf16 v[106:109], v[146:149], v[166:169], v[106:109]
	v_mfma_f32_16x16x32_bf16 v[94:97], v[138:141], v[174:177], v[94:97]
	v_mfma_f32_16x16x32_bf16 v[90:93], v[146:149], v[174:177], v[90:93]
	v_mfma_f32_16x16x32_bf16 v[78:81], v[138:141], v[182:185], v[78:81]
	v_mfma_f32_16x16x32_bf16 v[74:77], v[146:149], v[182:185], v[74:77]
	v_mfma_f32_16x16x32_bf16 v[126:129], v[142:145], v[162:165], v[126:129]
	v_mfma_f32_16x16x32_bf16 v[122:125], v[154:157], v[162:165], v[122:125]
	v_mfma_f32_16x16x32_bf16 v[110:113], v[142:145], v[170:173], v[110:113]
	v_mfma_f32_16x16x32_bf16 v[106:109], v[154:157], v[170:173], v[106:109]
	v_mfma_f32_16x16x32_bf16 v[94:97], v[142:145], v[178:181], v[94:97]
	v_mfma_f32_16x16x32_bf16 v[90:93], v[154:157], v[178:181], v[90:93]
	v_mfma_f32_16x16x32_bf16 v[78:81], v[142:145], v[186:189], v[78:81]
	v_mfma_f32_16x16x32_bf16 v[74:77], v[154:157], v[186:189], v[74:77]
	s_barrier
	s_add_i32 s24, 0, 0x1c000
	s_add_i32 s18, s43, s30
	v_add_u32_e32 v0, s24, v151
	v_lshl_add_u64 v[206:207], v[206:207], 0, s[46:47]
	s_mov_b32 m0, s18
	ds_read_b128 v[190:193], v0
	ds_read_b128 v[194:197], v0 offset:1024
	ds_read_b128 v[198:201], v0 offset:2048
	ds_read_b128 v[202:205], v0 offset:3072
	global_load_lds_dwordx4 v[206:207], off
	v_lshl_add_u64 v[206:207], v[208:209], 0, s[46:47]
	s_add_i32 m0, s18, 0x2000
	s_nop 0
	global_load_lds_dwordx4 v[206:207], off
	s_barrier
	s_waitcnt lgkmcnt(0)
	v_mfma_f32_16x16x32_bf16 v[118:121], v[190:193], v[158:161], v[118:121]
	v_mfma_f32_16x16x32_bf16 v[114:117], v[198:201], v[158:161], v[114:117]
	v_mfma_f32_16x16x32_bf16 v[102:105], v[190:193], v[166:169], v[102:105]
	v_mfma_f32_16x16x32_bf16 v[98:101], v[198:201], v[166:169], v[98:101]
	v_mfma_f32_16x16x32_bf16 v[86:89], v[190:193], v[174:177], v[86:89]
	v_mfma_f32_16x16x32_bf16 v[82:85], v[198:201], v[174:177], v[82:85]
	v_mfma_f32_16x16x32_bf16 v[70:73], v[190:193], v[182:185], v[70:73]
	v_mfma_f32_16x16x32_bf16 v[66:69], v[198:201], v[182:185], v[66:69]
	v_mfma_f32_16x16x32_bf16 v[118:121], v[194:197], v[162:165], v[118:121]
	v_mfma_f32_16x16x32_bf16 v[114:117], v[202:205], v[162:165], v[114:117]
	v_mfma_f32_16x16x32_bf16 v[102:105], v[194:197], v[170:173], v[102:105]
	v_mfma_f32_16x16x32_bf16 v[98:101], v[202:205], v[170:173], v[98:101]
	v_mfma_f32_16x16x32_bf16 v[86:89], v[194:197], v[178:181], v[86:89]
	v_mfma_f32_16x16x32_bf16 v[82:85], v[202:205], v[178:181], v[82:85]
	v_mfma_f32_16x16x32_bf16 v[70:73], v[194:197], v[186:189], v[70:73]
	v_mfma_f32_16x16x32_bf16 v[66:69], v[202:205], v[186:189], v[66:69]
	s_mov_b32 m0, s38
	v_lshl_add_u64 v[206:207], v[210:211], 0, s[46:47]
	s_barrier
	ds_read_b128 v[158:161], v153 offset:49152
	ds_read_b128 v[162:165], v153 offset:50176
	ds_read_b128 v[166:169], v153 offset:51200
	ds_read_b128 v[170:173], v153 offset:52224
	ds_read_b128 v[174:177], v153 offset:53248
	ds_read_b128 v[178:181], v153 offset:54272
	ds_read_b128 v[182:185], v153 offset:55296
	ds_read_b128 v[186:189], v153 offset:56320
	global_load_lds_dwordx4 v[206:207], off
	v_lshl_add_u64 v[206:207], v[220:221], 0, s[46:47]
	s_mov_b32 m0, s39
	s_nop 0
	global_load_lds_dwordx4 v[206:207], off
	s_barrier
; #define PG8_STAGE(bufoff, gbase, voff) do { _Pragma("unroll") for (int _i = 0; _i < 2; ++_i) \
;         __builtin_amdgcn_global_load_lds((const unsigned*)((const char*)(gbase) + (voff)[_i]), (LAS unsigned*)(lds + (bufoff) + ldsw + _i * 8192), 16, 0, 0); } while (0)
; #define PG8_LDA(dst, b, h) do { _Pragma("unroll") for (int m = 0; m < 4; ++m) _Pragma("unroll") for (int k = 0; k < 2; ++k) dst[m][k] = *(const LAS bf16x8*)(lds + PG8_SA(b, h) + aoff + m * 2048 + k * 1024); } while (0)
; #define PG8_MMA(ai, bj, At, Bt) do { __builtin_amdgcn_s_setprio(1); _Pragma("unroll") for (int m = 0; m < 4; ++m) _Pragma("unroll") for (int n = 0; n < 2; ++n) _Pragma("unroll") for (int k = 0; k < 2; ++k) \
;         acc[ai][bj][m][n] = __builtin_amdgcn_mfma_f32_16x16x32_bf16(Bt[n][k], At[m][k], acc[ai][bj][m][n], 0, 0, 0); __builtin_amdgcn_s_setprio(0); } while (0)
; template <class Epi, class Sched>
; __device__ __forceinline__ void gemm_phase(LAS unsigned char* lds, const Gemm g, const Sched& S, const Epi& E) {
;     ...
;             PG8_LDA(At, 1, 1); PG8_STAGE(PG8_SA(1, 0), a3, voffA);
;             PG8_BAR; PG8_WAIT_L(0); PG8_MMA(1, 0, At, B0); PG8_BAR; PG8_SCHED;
;             PG8_STAGE(PG8_SB(1, 1), b3 + hstep, voffB);
;             PG8_WAIT_V(6); PG8_BAR; PG8_MMA(1, 1, At, B1); PG8_BAR;
;     __device__ __forceinline__ void operator()(const f32x4 (&acc)[2][2][4][2], const pg8::Unit& u, int wr, int wc, int fr, int fq) const {
;         const int row0 = u.pm * 256 + wr * 64 + fr; const int col0 = u.pn * 256 + wc * 32 + 4 * fq;
; #pragma unroll
;         for (int ai = 0; ai < 2; ++ai)
; #pragma unroll
;             for (int m = 0; m < 4; ++m) { const int row = row0 + ai * 128 + m * 16;
;                 const float* ip; float* op; int b;
;                 if (row < ML_ROWS) { b = row >> 11; ip = xi + (size_t)row * D; op = xo + (size_t)row * D; }
;                 else { b = 8; ip = ci + (size_t)(row - ML_ROWS) * D; op = co + (size_t)(row - ML_ROWS) * D; }
;                 const float* gp = mod + (size_t)b * 12288 + slot * 2048;
; #pragma unroll
;                 for (int bj = 0; bj < 2; ++bj)
; #pragma unroll
;                     for (int n = 0; n < 2; ++n) { const int c = col0 + bj * 128 + n * 16;
;                         const f32x4 r = *(const f32x4*)(ip + c), g = *(const f32x4*)(gp + c);
;                         *(f32x4*)(op + c) = r + g * acc[ai][bj][m][n]; } }
	s_waitcnt lgkmcnt(0)
	v_mfma_f32_16x16x32_bf16 v[62:65], v[138:141], v[158:161], v[62:65]
	v_mfma_f32_16x16x32_bf16 v[58:61], v[146:149], v[158:161], v[58:61]
	v_mfma_f32_16x16x32_bf16 v[46:49], v[138:141], v[166:169], v[46:49]
	v_mfma_f32_16x16x32_bf16 v[42:45], v[146:149], v[166:169], v[42:45]
	v_mfma_f32_16x16x32_bf16 v[30:33], v[138:141], v[174:177], v[30:33]
	v_mfma_f32_16x16x32_bf16 v[26:29], v[146:149], v[174:177], v[26:29]
	v_mfma_f32_16x16x32_bf16 v[14:17], v[138:141], v[182:185], v[14:17]
	v_mfma_f32_16x16x32_bf16 v[10:13], v[146:149], v[182:185], v[10:13]
	v_mfma_f32_16x16x32_bf16 v[62:65], v[142:145], v[162:165], v[62:65]
	v_mfma_f32_16x16x32_bf16 v[58:61], v[154:157], v[162:165], v[58:61]
	v_mfma_f32_16x16x32_bf16 v[46:49], v[142:145], v[170:173], v[46:49]
	v_mfma_f32_16x16x32_bf16 v[42:45], v[154:157], v[170:173], v[42:45]
	v_mfma_f32_16x16x32_bf16 v[30:33], v[142:145], v[178:181], v[30:33]
	v_mfma_f32_16x16x32_bf16 v[26:29], v[154:157], v[178:181], v[26:29]
	v_mfma_f32_16x16x32_bf16 v[14:17], v[142:145], v[186:189], v[14:17]
	v_mfma_f32_16x16x32_bf16 v[10:13], v[154:157], v[186:189], v[10:13]
	s_barrier
	s_add_u32 s18, s22, 0x80080
	s_addc_u32 s19, s23, 0
	s_add_i32 s22, s24, s30
	s_mov_b32 m0, s22
	s_nop 0
	global_load_lds_dwordx4 v130, s[18:19]
	s_add_i32 m0, s22, 0x2000
	s_nop 0
	global_load_lds_dwordx4 v132, s[18:19]
	s_waitcnt vmcnt(6)
	s_barrier
	v_mfma_f32_16x16x32_bf16 v[54:57], v[190:193], v[158:161], v[54:57]
	v_mfma_f32_16x16x32_bf16 v[50:53], v[198:201], v[158:161], v[50:53]
	v_mfma_f32_16x16x32_bf16 v[38:41], v[190:193], v[166:169], v[38:41]
	v_mfma_f32_16x16x32_bf16 v[34:37], v[198:201], v[166:169], v[34:37]
	v_mfma_f32_16x16x32_bf16 v[22:25], v[190:193], v[174:177], v[22:25]
	v_mfma_f32_16x16x32_bf16 v[18:21], v[198:201], v[174:177], v[18:21]
	v_mfma_f32_16x16x32_bf16 v[6:9], v[190:193], v[182:185], v[6:9]
	v_mfma_f32_16x16x32_bf16 v[2:5], v[198:201], v[182:185], v[2:5]
	v_mfma_f32_16x16x32_bf16 v[54:57], v[194:197], v[162:165], v[54:57]
	v_mfma_f32_16x16x32_bf16 v[50:53], v[202:205], v[162:165], v[50:53]
	v_mfma_f32_16x16x32_bf16 v[38:41], v[194:197], v[170:173], v[38:41]
	v_mfma_f32_16x16x32_bf16 v[34:37], v[202:205], v[170:173], v[34:37]
	v_mfma_f32_16x16x32_bf16 v[22:25], v[194:197], v[178:181], v[22:25]
	v_mfma_f32_16x16x32_bf16 v[18:21], v[202:205], v[178:181], v[18:21]
	v_mfma_f32_16x16x32_bf16 v[6:9], v[194:197], v[186:189], v[6:9]
	v_mfma_f32_16x16x32_bf16 v[2:5], v[202:205], v[186:189], v[2:5]
	s_add_i32 s42, s42, 2
	s_add_u32 s17, s17, 0x100
	s_addc_u32 s41, s41, 0
	s_cmp_gt_u32 s42, 29
	s_mov_b64 s[18:19], s[20:21]
	s_barrier
	s_cbranch_scc0 .LBB0_1123
	s_lshl_b32 s1, s16, 8
	s_add_i32 s1, s1, s37
	v_readlane_b32 s44, v251, 0
	v_readlane_b32 s45, v251, 1
	v_readlane_b32 s46, v251, 2
	v_readlane_b32 s47, v251, 3
	v_readlane_b32 s48, v251, 4
	v_readlane_b32 s49, v251, 5
	v_readlane_b32 s50, v251, 6
	v_readlane_b32 s51, v251, 7
	v_readlane_b32 s22, v254, 4
	v_readlane_b32 s23, v254, 5
	v_readlane_b32 s20, v254, 6
	v_readlane_b32 s21, v254, 7
	v_readlane_b32 s18, v254, 2
	v_readlane_b32 s19, v254, 3
	s_add_i32 s3, s1, 0xffffc000
	s_ashr_i32 s15, s1, 11
	s_cmpk_lt_i32 s1, 0x4000
	s_cselect_b32 s22, s22, s20
	s_cselect_b32 s23, s23, s21
	s_cselect_b32 s20, s46, s60
	s_cselect_b32 s21, s47, s61
	s_cselect_b32 s3, s1, s3
	s_cselect_b32 s15, s15, 8
	s_mul_i32 s15, s15, 0xc000
	s_add_u32 s18, s18, s15
	s_addc_u32 s19, s19, 0
	s_add_u32 s18, s18, 0x4000
	s_addc_u32 s19, s19, 0
	v_add_u32_e32 v138, s3, v150
	v_lshl_or_b32 v139, s14, 8, v152
	v_lshlrev_b32_e32 v139, 2, v139
	v_lshl_or_b32 v138, v138, 13, v139
	v_add_u32_e32 v140, 0x20000, v138
	v_add_u32_e32 v141, 0x40000, v138
	v_add_u32_e32 v0, 0x60000, v138
	v_add_u32_e32 v210, 0x100000, v138
	v_add_u32_e32 v211, 0x120000, v138
	v_add_u32_e32 v220, 0x140000, v138
	global_load_dwordx4 v[154:157], v139, s[18:19]
	global_load_dwordx4 v[158:161], v139, s[18:19] offset:64
	global_load_dwordx4 v[162:165], v139, s[18:19] offset:512
	global_load_dwordx4 v[166:169], v139, s[18:19] offset:576
	v_add_u32_e32 v139, 0x160000, v138
	global_load_dwordx4 v[170:173], v138, s[22:23]
	global_load_dwordx4 v[174:177], v138, s[22:23] offset:64
	global_load_dwordx4 v[178:181], v138, s[22:23] offset:512
	global_load_dwordx4 v[182:185], v138, s[22:23] offset:576
	global_load_dwordx4 v[186:189], v140, s[22:23]
	global_load_dwordx4 v[190:193], v140, s[22:23] offset:64
	global_load_dwordx4 v[194:197], v140, s[22:23] offset:512
	global_load_dwordx4 v[198:201], v140, s[22:23] offset:576
	global_load_dwordx4 v[202:205], v141, s[22:23]
	global_load_dwordx4 v[206:209], v141, s[22:23] offset:64
	global_load_dwordx4 v[142:145], v141, s[22:23] offset:512
	global_load_dwordx4 v[146:149], v141, s[22:23] offset:576
	s_waitcnt vmcnt(8)
	v_pk_fma_f32 v[126:127], v[126:127], v[154:155], v[170:171]
	v_pk_fma_f32 v[128:129], v[128:129], v[156:157], v[172:173]
	v_pk_fma_f32 v[122:123], v[122:123], v[158:159], v[174:175]
	v_pk_fma_f32 v[124:125], v[124:125], v[160:161], v[176:177]
	v_pk_fma_f32 v[118:119], v[118:119], v[162:163], v[178:179]
	v_pk_fma_f32 v[120:121], v[120:121], v[164:165], v[180:181]
	v_pk_fma_f32 v[114:115], v[114:115], v[166:167], v[182:183]
	v_pk_fma_f32 v[116:117], v[116:117], v[168:169], v[184:185]
	global_store_dwordx4 v138, v[126:129], s[20:21]
	global_store_dwordx4 v138, v[122:125], s[20:21] offset:64
	global_store_dwordx4 v138, v[118:121], s[20:21] offset:512
	global_store_dwordx4 v138, v[114:117], s[20:21] offset:576
	global_load_dwordx4 v[170:173], v0, s[22:23]
	global_load_dwordx4 v[174:177], v0, s[22:23] offset:64
	global_load_dwordx4 v[178:181], v0, s[22:23] offset:512
	global_load_dwordx4 v[182:185], v0, s[22:23] offset:576
	s_waitcnt vmcnt(12)
;     __device__ __forceinline__ void operator()(const f32x4 (&acc)[2][2][4][2], const pg8::Unit& u, int wr, int wc, int fr, int fq) const {
;     ...
;             for (int m = 0; m < 4; ++m) { const int row = row0 + ai * 128 + m * 16;
;                 const float* ip; float* op; int b;
;                 if (row < ML_ROWS) { b = row >> 11; ip = xi + (size_t)row * D; op = xo + (size_t)row * D; }
;                 else { b = 8; ip = ci + (size_t)(row - ML_ROWS) * D; op = co + (size_t)(row - ML_ROWS) * D; }
;                 const float* gp = mod + (size_t)b * 12288 + slot * 2048;
; #pragma unroll
;                 for (int bj = 0; bj < 2; ++bj)
; #pragma unroll
;                     for (int n = 0; n < 2; ++n) { const int c = col0 + bj * 128 + n * 16;
;                         const f32x4 r = *(const f32x4*)(ip + c), g = *(const f32x4*)(gp + c);
;                         *(f32x4*)(op + c) = r + g * acc[ai][bj][m][n]; } }
	v_pk_fma_f32 v[110:111], v[110:111], v[154:155], v[186:187]
	v_pk_fma_f32 v[112:113], v[112:113], v[156:157], v[188:189]
	v_pk_fma_f32 v[106:107], v[106:107], v[158:159], v[190:191]
	v_pk_fma_f32 v[108:109], v[108:109], v[160:161], v[192:193]
	v_pk_fma_f32 v[102:103], v[102:103], v[162:163], v[194:195]
	v_pk_fma_f32 v[104:105], v[104:105], v[164:165], v[196:197]
	v_pk_fma_f32 v[98:99], v[98:99], v[166:167], v[198:199]
	v_pk_fma_f32 v[100:101], v[100:101], v[168:169], v[200:201]
	global_store_dwordx4 v140, v[110:113], s[20:21]
	global_store_dwordx4 v140, v[106:109], s[20:21] offset:64
	global_store_dwordx4 v140, v[102:105], s[20:21] offset:512
	global_store_dwordx4 v140, v[98:101], s[20:21] offset:576
	global_load_dwordx4 v[186:189], v210, s[22:23]
	global_load_dwordx4 v[190:193], v210, s[22:23] offset:64
	global_load_dwordx4 v[194:197], v210, s[22:23] offset:512
	global_load_dwordx4 v[198:201], v210, s[22:23] offset:576
	s_waitcnt vmcnt(16)
	v_pk_fma_f32 v[94:95], v[94:95], v[154:155], v[202:203]
	v_pk_fma_f32 v[96:97], v[96:97], v[156:157], v[204:205]
	v_pk_fma_f32 v[90:91], v[90:91], v[158:159], v[206:207]
	v_pk_fma_f32 v[92:93], v[92:93], v[160:161], v[208:209]
	v_pk_fma_f32 v[86:87], v[86:87], v[162:163], v[142:143]
	v_pk_fma_f32 v[88:89], v[88:89], v[164:165], v[144:145]
	v_pk_fma_f32 v[82:83], v[82:83], v[166:167], v[146:147]
	v_pk_fma_f32 v[84:85], v[84:85], v[168:169], v[148:149]
	global_store_dwordx4 v141, v[94:97], s[20:21]
	global_store_dwordx4 v141, v[90:93], s[20:21] offset:64
	global_store_dwordx4 v141, v[86:89], s[20:21] offset:512
	global_store_dwordx4 v141, v[82:85], s[20:21] offset:576
	global_load_dwordx4 v[202:205], v211, s[22:23]
	global_load_dwordx4 v[206:209], v211, s[22:23] offset:64
	global_load_dwordx4 v[142:145], v211, s[22:23] offset:512
	global_load_dwordx4 v[146:149], v211, s[22:23] offset:576
	s_waitcnt vmcnt(16)
	v_pk_fma_f32 v[78:79], v[78:79], v[154:155], v[170:171]
	v_pk_fma_f32 v[80:81], v[80:81], v[156:157], v[172:173]
	v_pk_fma_f32 v[74:75], v[74:75], v[158:159], v[174:175]
	v_pk_fma_f32 v[76:77], v[76:77], v[160:161], v[176:177]
	v_pk_fma_f32 v[70:71], v[70:71], v[162:163], v[178:179]
	v_pk_fma_f32 v[72:73], v[72:73], v[164:165], v[180:181]
	v_pk_fma_f32 v[66:67], v[66:67], v[166:167], v[182:183]
	v_pk_fma_f32 v[68:69], v[68:69], v[168:169], v[184:185]
	global_store_dwordx4 v0, v[78:81], s[20:21]
	global_store_dwordx4 v0, v[74:77], s[20:21] offset:64
	global_store_dwordx4 v0, v[70:73], s[20:21] offset:512
	global_store_dwordx4 v0, v[66:69], s[20:21] offset:576
	global_load_dwordx4 v[170:173], v220, s[22:23]
	global_load_dwordx4 v[174:177], v220, s[22:23] offset:64
	global_load_dwordx4 v[178:181], v220, s[22:23] offset:512
	global_load_dwordx4 v[182:185], v220, s[22:23] offset:576
	s_waitcnt vmcnt(16)
	v_pk_fma_f32 v[62:63], v[62:63], v[154:155], v[186:187]
	v_pk_fma_f32 v[64:65], v[64:65], v[156:157], v[188:189]
	v_pk_fma_f32 v[58:59], v[58:59], v[158:159], v[190:191]
	v_pk_fma_f32 v[60:61], v[60:61], v[160:161], v[192:193]
	v_pk_fma_f32 v[54:55], v[54:55], v[162:163], v[194:195]
	v_pk_fma_f32 v[56:57], v[56:57], v[164:165], v[196:197]
	v_pk_fma_f32 v[50:51], v[50:51], v[166:167], v[198:199]
	v_pk_fma_f32 v[52:53], v[52:53], v[168:169], v[200:201]
	global_store_dwordx4 v210, v[62:65], s[20:21]
	global_store_dwordx4 v210, v[58:61], s[20:21] offset:64
	global_store_dwordx4 v210, v[54:57], s[20:21] offset:512
	global_store_dwordx4 v210, v[50:53], s[20:21] offset:576
	global_load_dwordx4 v[186:189], v139, s[22:23]
	global_load_dwordx4 v[190:193], v139, s[22:23] offset:64
	global_load_dwordx4 v[194:197], v139, s[22:23] offset:512
	global_load_dwordx4 v[198:201], v139, s[22:23] offset:576
	s_waitcnt vmcnt(16)
	v_pk_fma_f32 v[46:47], v[46:47], v[154:155], v[202:203]
	v_pk_fma_f32 v[48:49], v[48:49], v[156:157], v[204:205]
	v_pk_fma_f32 v[42:43], v[42:43], v[158:159], v[206:207]
	v_pk_fma_f32 v[44:45], v[44:45], v[160:161], v[208:209]
	v_pk_fma_f32 v[38:39], v[38:39], v[162:163], v[142:143]
	v_pk_fma_f32 v[40:41], v[40:41], v[164:165], v[144:145]
	v_pk_fma_f32 v[34:35], v[34:35], v[166:167], v[146:147]
	v_pk_fma_f32 v[36:37], v[36:37], v[168:169], v[148:149]
	global_store_dwordx4 v211, v[46:49], s[20:21]
	global_store_dwordx4 v211, v[42:45], s[20:21] offset:64
	global_store_dwordx4 v211, v[38:41], s[20:21] offset:512
	global_store_dwordx4 v211, v[34:37], s[20:21] offset:576
	s_waitcnt vmcnt(12)
	v_pk_fma_f32 v[30:31], v[30:31], v[154:155], v[170:171]
	v_pk_fma_f32 v[32:33], v[32:33], v[156:157], v[172:173]
	v_pk_fma_f32 v[26:27], v[26:27], v[158:159], v[174:175]
	v_pk_fma_f32 v[28:29], v[28:29], v[160:161], v[176:177]
	v_pk_fma_f32 v[22:23], v[22:23], v[162:163], v[178:179]
	v_pk_fma_f32 v[24:25], v[24:25], v[164:165], v[180:181]
	v_pk_fma_f32 v[18:19], v[18:19], v[166:167], v[182:183]
	v_pk_fma_f32 v[20:21], v[20:21], v[168:169], v[184:185]
	global_store_dwordx4 v220, v[30:33], s[20:21]
	global_store_dwordx4 v220, v[26:29], s[20:21] offset:64
	global_store_dwordx4 v220, v[22:25], s[20:21] offset:512
	global_store_dwordx4 v220, v[18:21], s[20:21] offset:576
	s_waitcnt vmcnt(8)
	v_pk_fma_f32 v[14:15], v[14:15], v[154:155], v[186:187]
	v_pk_fma_f32 v[16:17], v[16:17], v[156:157], v[188:189]
	v_pk_fma_f32 v[10:11], v[10:11], v[158:159], v[190:191]
	v_pk_fma_f32 v[12:13], v[12:13], v[160:161], v[192:193]
	v_pk_fma_f32 v[6:7], v[6:7], v[162:163], v[194:195]
	v_pk_fma_f32 v[8:9], v[8:9], v[164:165], v[196:197]
	v_pk_fma_f32 v[2:3], v[2:3], v[166:167], v[198:199]
	v_pk_fma_f32 v[4:5], v[4:5], v[168:169], v[200:201]
	global_store_dwordx4 v139, v[14:17], s[20:21]
	global_store_dwordx4 v139, v[10:13], s[20:21] offset:64
	global_store_dwordx4 v139, v[6:9], s[20:21] offset:512
	global_store_dwordx4 v139, v[2:5], s[20:21] offset:576
	v_mov_b32_e32 v170, v219
	s_mov_b32 s14, s0
	s_mov_b32 s16, s8
	s_mov_b64 s[20:21], s[12:13]
	s_mov_b64 s[18:19], s[10:11]
	s_and_b64 vcc, exec, s[4:5]
	s_cbranch_vccnz .LBB0_1156
	s_branch .LBB0_1120

; #define PG8_STAGE(bufoff, gbase, voff) do { _Pragma("unroll") for (int _i = 0; _i < 2; ++_i) \
;         __builtin_amdgcn_global_load_lds((const unsigned*)((const char*)(gbase) + (voff)[_i]), (LAS unsigned*)(lds + (bufoff) + ldsw + _i * 8192), 16, 0, 0); } while (0)
; #define PG8_LDA(dst, b, h) do { _Pragma("unroll") for (int m = 0; m < 4; ++m) _Pragma("unroll") for (int k = 0; k < 2; ++k) dst[m][k] = *(const LAS bf16x8*)(lds + PG8_SA(b, h) + aoff + m * 2048 + k * 1024); } while (0)
; #define PG8_LDB(dst, b, h) do { _Pragma("unroll") for (int n = 0; n < 2; ++n) _Pragma("unroll") for (int k = 0; k < 2; ++k) dst[n][k] = *(const LAS bf16x8*)(lds + PG8_SB(b, h) + boff + n * 2048 + k * 1024); } while (0)
; #define PG8_MMA(ai, bj, At, Bt) do { __builtin_amdgcn_s_setprio(1); _Pragma("unroll") for (int m = 0; m < 4; ++m) _Pragma("unroll") for (int n = 0; n < 2; ++n) _Pragma("unroll") for (int k = 0; k < 2; ++k) \
;         acc[ai][bj][m][n] = __builtin_amdgcn_mfma_f32_16x16x32_bf16(Bt[n][k], At[m][k], acc[ai][bj][m][n], 0, 0, 0); __builtin_amdgcn_s_setprio(0); } while (0)
; #define PG8_WAIT_V(n) asm volatile("s_waitcnt vmcnt(" #n ")" ::: "memory")
; #define PG8_WAIT_L(n) asm volatile("s_waitcnt lgkmcnt(" #n ")" ::: "memory")
; #define PG8_BAR __builtin_amdgcn_s_barrier()
; #define PG8_SCHED __builtin_amdgcn_sched_barrier(0)
; template <class Epi, class Sched>
; __device__ __forceinline__ void gemm_phase(LAS unsigned char* lds, const Gemm g, const Sched& S, const Epi& E) {
;     ...
;             PG8_LDB(B0, 0, 0); PG8_SCHED; PG8_LDA(At, 0, 0); PG8_STAGE(PG8_SA(1, 1), a1 + hstep, voffA);
;             PG8_WAIT_L(8); PG8_BAR; PG8_WAIT_L(0); PG8_MMA(0, 0, At, B0); PG8_BAR; PG8_SCHED;
;             PG8_LDB(B1, 0, 1); PG8_STAGE(PG8_SB(0, 0), b2, voffB);
;             PG8_BAR; PG8_WAIT_L(0); PG8_MMA(0, 1, At, B1); PG8_BAR;
;             PG8_LDA(At, 0, 1); PG8_STAGE(PG8_SA(0, 0), a2, voffA);
;             PG8_BAR; PG8_WAIT_L(0); PG8_MMA(1, 0, At, B0); PG8_BAR; PG8_SCHED;
;             PG8_STAGE(PG8_SB(0, 1), b2 + hstep, voffB);
;             PG8_WAIT_V(6); PG8_BAR; PG8_MMA(1, 1, At, B1); PG8_BAR;
.LBB0_1279:
	s_nop 0
	v_add_u32_e32 v140, s47, v143
	ds_read_b128 v[146:149], v140
	ds_read_b128 v[150:153], v140 offset:1024
	ds_read_b128 v[154:157], v140 offset:2048
	ds_read_b128 v[158:161], v140 offset:3072
	s_add_u32 s22, s20, 0xfff80080
	s_addc_u32 s23, s21, -1
	s_cmp_eq_u32 s43, 28
	s_cselect_b32 s25, s3, s23
	s_cselect_b32 s24, s11, s22
	s_cselect_b32 s23, s9, s42
	s_cselect_b32 s22, s40, s41
	s_add_i32 m0, s17, 0xc000
	ds_read_b128 v[162:165], v145
	ds_read_b128 v[166:169], v145 offset:1024
	ds_read_b128 v[170:173], v145 offset:2048
	ds_read_b128 v[174:177], v145 offset:3072
	ds_read_b128 v[178:181], v145 offset:4096
	ds_read_b128 v[182:185], v145 offset:5120
	ds_read_b128 v[186:189], v145 offset:6144
	ds_read_b128 v[190:193], v145 offset:7168
	global_load_lds_dwordx4 v136, s[20:21]
	s_add_i32 m0, s17, 0xe000
	s_nop 0
	global_load_lds_dwordx4 v138, s[20:21]
	s_waitcnt lgkmcnt(8)
	s_barrier
	s_waitcnt lgkmcnt(0)
	v_mfma_f32_16x16x32_bf16 v[126:129], v[146:149], v[162:165], v[126:129]
	v_mfma_f32_16x16x32_bf16 v[122:125], v[154:157], v[162:165], v[122:125]
	v_mfma_f32_16x16x32_bf16 v[110:113], v[146:149], v[170:173], v[110:113]
	v_mfma_f32_16x16x32_bf16 v[106:109], v[154:157], v[170:173], v[106:109]
	v_mfma_f32_16x16x32_bf16 v[94:97], v[146:149], v[178:181], v[94:97]
	v_mfma_f32_16x16x32_bf16 v[90:93], v[154:157], v[178:181], v[90:93]
	v_mfma_f32_16x16x32_bf16 v[78:81], v[146:149], v[186:189], v[78:81]
	v_mfma_f32_16x16x32_bf16 v[74:77], v[154:157], v[186:189], v[74:77]
	v_mfma_f32_16x16x32_bf16 v[126:129], v[150:153], v[166:169], v[126:129]
	v_mfma_f32_16x16x32_bf16 v[122:125], v[158:161], v[166:169], v[122:125]
	v_mfma_f32_16x16x32_bf16 v[110:113], v[150:153], v[174:177], v[110:113]
	v_mfma_f32_16x16x32_bf16 v[106:109], v[158:161], v[174:177], v[106:109]
	v_mfma_f32_16x16x32_bf16 v[94:97], v[150:153], v[182:185], v[94:97]
	v_mfma_f32_16x16x32_bf16 v[90:93], v[158:161], v[182:185], v[90:93]
	v_mfma_f32_16x16x32_bf16 v[78:81], v[150:153], v[190:193], v[78:81]
	v_mfma_f32_16x16x32_bf16 v[74:77], v[158:161], v[190:193], v[74:77]
	s_barrier
	s_add_i32 s46, 0, 0x14000
	v_add_u32_e32 v140, s46, v143
	s_add_i32 s44, s47, s30
	ds_read_b128 v[194:197], v140
	ds_read_b128 v[198:201], v140 offset:1024
	ds_read_b128 v[202:205], v140 offset:2048
	ds_read_b128 v[206:209], v140 offset:3072
	v_lshl_add_u64 v[140:141], s[22:23], 0, v[0:1]
	s_mov_b32 m0, s44
	v_lshl_add_u64 v[210:211], s[22:23], 0, v[130:131]
	global_load_lds_dwordx4 v[140:141], off
	s_add_i32 m0, s44, 0x2000
	s_nop 0
	global_load_lds_dwordx4 v[210:211], off
	s_barrier
	s_waitcnt lgkmcnt(0)
	v_mfma_f32_16x16x32_bf16 v[118:121], v[194:197], v[162:165], v[118:121]
	v_mfma_f32_16x16x32_bf16 v[114:117], v[202:205], v[162:165], v[114:117]
	v_mfma_f32_16x16x32_bf16 v[102:105], v[194:197], v[170:173], v[102:105]
	v_mfma_f32_16x16x32_bf16 v[98:101], v[202:205], v[170:173], v[98:101]
	v_mfma_f32_16x16x32_bf16 v[86:89], v[194:197], v[178:181], v[86:89]
	v_mfma_f32_16x16x32_bf16 v[82:85], v[202:205], v[178:181], v[82:85]
	v_mfma_f32_16x16x32_bf16 v[70:73], v[194:197], v[186:189], v[70:73]
	v_mfma_f32_16x16x32_bf16 v[66:69], v[202:205], v[186:189], v[66:69]
	v_mfma_f32_16x16x32_bf16 v[118:121], v[198:201], v[166:169], v[118:121]
	v_mfma_f32_16x16x32_bf16 v[114:117], v[206:209], v[166:169], v[114:117]
	v_mfma_f32_16x16x32_bf16 v[102:105], v[198:201], v[174:177], v[102:105]
	v_mfma_f32_16x16x32_bf16 v[98:101], v[206:209], v[174:177], v[98:101]
	v_mfma_f32_16x16x32_bf16 v[86:89], v[198:201], v[182:185], v[86:89]
	v_mfma_f32_16x16x32_bf16 v[82:85], v[206:209], v[182:185], v[82:85]
	v_mfma_f32_16x16x32_bf16 v[70:73], v[198:201], v[190:193], v[70:73]
	v_mfma_f32_16x16x32_bf16 v[66:69], v[206:209], v[190:193], v[66:69]
	s_mov_b32 m0, s17
	v_lshl_add_u64 v[220:221], s[24:25], 0, v[134:135]
	s_barrier
	ds_read_b128 v[162:165], v145 offset:16384
	ds_read_b128 v[166:169], v145 offset:17408
	ds_read_b128 v[170:173], v145 offset:18432
	ds_read_b128 v[174:177], v145 offset:19456
	ds_read_b128 v[178:181], v145 offset:20480
	ds_read_b128 v[182:185], v145 offset:21504
	ds_read_b128 v[186:189], v145 offset:22528
	ds_read_b128 v[190:193], v145 offset:23552
	global_load_lds_dwordx4 v[220:221], off
	v_lshl_add_u64 v[222:223], s[24:25], 0, v[132:133]
	s_mov_b32 m0, s19
	s_nop 0
	global_load_lds_dwordx4 v[222:223], off
	s_barrier
	s_waitcnt lgkmcnt(0)
	v_mfma_f32_16x16x32_bf16 v[62:65], v[146:149], v[162:165], v[62:65]
	v_mfma_f32_16x16x32_bf16 v[58:61], v[154:157], v[162:165], v[58:61]
	v_mfma_f32_16x16x32_bf16 v[46:49], v[146:149], v[170:173], v[46:49]
	v_mfma_f32_16x16x32_bf16 v[42:45], v[154:157], v[170:173], v[42:45]
	v_mfma_f32_16x16x32_bf16 v[30:33], v[146:149], v[178:181], v[30:33]
	v_mfma_f32_16x16x32_bf16 v[26:29], v[154:157], v[178:181], v[26:29]
	v_mfma_f32_16x16x32_bf16 v[14:17], v[146:149], v[186:189], v[14:17]
	v_mfma_f32_16x16x32_bf16 v[10:13], v[154:157], v[186:189], v[10:13]
	v_mfma_f32_16x16x32_bf16 v[62:65], v[150:153], v[166:169], v[62:65]
	v_mfma_f32_16x16x32_bf16 v[58:61], v[158:161], v[166:169], v[58:61]
	v_mfma_f32_16x16x32_bf16 v[46:49], v[150:153], v[174:177], v[46:49]
	v_mfma_f32_16x16x32_bf16 v[42:45], v[158:161], v[174:177], v[42:45]
	v_mfma_f32_16x16x32_bf16 v[30:33], v[150:153], v[182:185], v[30:33]
	v_mfma_f32_16x16x32_bf16 v[26:29], v[158:161], v[182:185], v[26:29]
	v_mfma_f32_16x16x32_bf16 v[14:17], v[150:153], v[190:193], v[14:17]
	v_mfma_f32_16x16x32_bf16 v[10:13], v[158:161], v[190:193], v[10:13]
	s_barrier
	s_add_u32 s44, s22, 0x80000
	s_addc_u32 s45, s23, 0
	s_add_i32 s46, s46, s30
	s_mov_b32 m0, s46
	s_nop 0
	global_load_lds_dwordx4 v0, s[44:45]
	s_add_i32 m0, s46, 0x2000
	s_nop 0
	global_load_lds_dwordx4 v130, s[44:45]
	s_waitcnt vmcnt(6)
	s_barrier
; #define PG8_STAGE(bufoff, gbase, voff) do { _Pragma("unroll") for (int _i = 0; _i < 2; ++_i) \
;         __builtin_amdgcn_global_load_lds((const unsigned*)((const char*)(gbase) + (voff)[_i]), (LAS unsigned*)(lds + (bufoff) + ldsw + _i * 8192), 16, 0, 0); } while (0)
; #define PG8_LDA(dst, b, h) do { _Pragma("unroll") for (int m = 0; m < 4; ++m) _Pragma("unroll") for (int k = 0; k < 2; ++k) dst[m][k] = *(const LAS bf16x8*)(lds + PG8_SA(b, h) + aoff + m * 2048 + k * 1024); } while (0)
; #define PG8_LDB(dst, b, h) do { _Pragma("unroll") for (int n = 0; n < 2; ++n) _Pragma("unroll") for (int k = 0; k < 2; ++k) dst[n][k] = *(const LAS bf16x8*)(lds + PG8_SB(b, h) + boff + n * 2048 + k * 1024); } while (0)
; #define PG8_MMA(ai, bj, At, Bt) do { __builtin_amdgcn_s_setprio(1); _Pragma("unroll") for (int m = 0; m < 4; ++m) _Pragma("unroll") for (int n = 0; n < 2; ++n) _Pragma("unroll") for (int k = 0; k < 2; ++k) \
;         acc[ai][bj][m][n] = __builtin_amdgcn_mfma_f32_16x16x32_bf16(Bt[n][k], At[m][k], acc[ai][bj][m][n], 0, 0, 0); __builtin_amdgcn_s_setprio(0); } while (0)
; #define PG8_WAIT_V(n) asm volatile("s_waitcnt vmcnt(" #n ")" ::: "memory")
; #define PG8_WAIT_L(n) asm volatile("s_waitcnt lgkmcnt(" #n ")" ::: "memory")
; #define PG8_BAR __builtin_amdgcn_s_barrier()
; #define PG8_SCHED __builtin_amdgcn_sched_barrier(0)
; template <class Epi, class Sched>
; __device__ __forceinline__ void gemm_phase(LAS unsigned char* lds, const Gemm g, const Sched& S, const Epi& E) {
;     ...
;             PG8_STAGE(PG8_SB(0, 1), b2 + hstep, voffB);
;             PG8_WAIT_V(6); PG8_BAR; PG8_MMA(1, 1, At, B1); PG8_BAR;
;             PG8_LDB(B0, 1, 0); PG8_SCHED; PG8_LDA(At, 1, 0); PG8_STAGE(PG8_SA(0, 1), a2 + hstep, voffA);
;             PG8_WAIT_L(8); PG8_BAR; PG8_WAIT_L(0); PG8_MMA(0, 0, At, B0); PG8_BAR; PG8_SCHED;
;             PG8_LDB(B1, 1, 1); PG8_STAGE(PG8_SB(1, 0), b3, voffB);
;             PG8_BAR; PG8_WAIT_L(0); PG8_MMA(0, 1, At, B1); PG8_BAR;
;             PG8_LDA(At, 1, 1); PG8_STAGE(PG8_SA(1, 0), a3, voffA);
;             PG8_BAR; PG8_WAIT_L(0); PG8_MMA(1, 0, At, B0); PG8_BAR; PG8_SCHED;
	v_mfma_f32_16x16x32_bf16 v[54:57], v[194:197], v[162:165], v[54:57]
	v_mfma_f32_16x16x32_bf16 v[50:53], v[202:205], v[162:165], v[50:53]
	v_mfma_f32_16x16x32_bf16 v[38:41], v[194:197], v[170:173], v[38:41]
	v_mfma_f32_16x16x32_bf16 v[34:37], v[202:205], v[170:173], v[34:37]
	v_mfma_f32_16x16x32_bf16 v[22:25], v[194:197], v[178:181], v[22:25]
	v_mfma_f32_16x16x32_bf16 v[18:21], v[202:205], v[178:181], v[18:21]
	v_mfma_f32_16x16x32_bf16 v[6:9], v[194:197], v[186:189], v[6:9]
	v_mfma_f32_16x16x32_bf16 v[2:5], v[202:205], v[186:189], v[2:5]
	v_mfma_f32_16x16x32_bf16 v[54:57], v[198:201], v[166:169], v[54:57]
	v_mfma_f32_16x16x32_bf16 v[50:53], v[206:209], v[166:169], v[50:53]
	v_mfma_f32_16x16x32_bf16 v[38:41], v[198:201], v[174:177], v[38:41]
	v_mfma_f32_16x16x32_bf16 v[34:37], v[206:209], v[174:177], v[34:37]
	v_mfma_f32_16x16x32_bf16 v[22:25], v[198:201], v[182:185], v[22:25]
	v_mfma_f32_16x16x32_bf16 v[18:21], v[206:209], v[182:185], v[18:21]
	v_mfma_f32_16x16x32_bf16 v[6:9], v[198:201], v[190:193], v[6:9]
	v_mfma_f32_16x16x32_bf16 v[2:5], v[206:209], v[190:193], v[2:5]
	s_add_i32 s44, 0, 0x18000
	v_add_u32_e32 v158, s44, v143
	s_barrier
	ds_read_b128 v[146:149], v158
	ds_read_b128 v[150:153], v158 offset:1024
	ds_read_b128 v[154:157], v158 offset:2048
	ds_read_b128 v[158:161], v158 offset:3072
	s_add_u32 s24, s24, 0x80000
	s_addc_u32 s25, s25, 0
	s_mov_b32 m0, s35
	ds_read_b128 v[162:165], v145 offset:32768
	ds_read_b128 v[166:169], v145 offset:33792
	ds_read_b128 v[170:173], v145 offset:34816
	ds_read_b128 v[174:177], v145 offset:35840
	ds_read_b128 v[178:181], v145 offset:36864
	ds_read_b128 v[182:185], v145 offset:37888
	ds_read_b128 v[186:189], v145 offset:38912
	ds_read_b128 v[190:193], v145 offset:39936
	global_load_lds_dwordx4 v134, s[24:25]
	s_mov_b32 m0, s36
	s_nop 0
	global_load_lds_dwordx4 v132, s[24:25]
	s_waitcnt lgkmcnt(8)
	s_barrier
	s_waitcnt lgkmcnt(0)
	v_mfma_f32_16x16x32_bf16 v[126:129], v[146:149], v[162:165], v[126:129]
	v_mfma_f32_16x16x32_bf16 v[122:125], v[154:157], v[162:165], v[122:125]
	v_mfma_f32_16x16x32_bf16 v[110:113], v[146:149], v[170:173], v[110:113]
	v_mfma_f32_16x16x32_bf16 v[106:109], v[154:157], v[170:173], v[106:109]
	v_mfma_f32_16x16x32_bf16 v[94:97], v[146:149], v[178:181], v[94:97]
	v_mfma_f32_16x16x32_bf16 v[90:93], v[154:157], v[178:181], v[90:93]
	v_mfma_f32_16x16x32_bf16 v[78:81], v[146:149], v[186:189], v[78:81]
	v_mfma_f32_16x16x32_bf16 v[74:77], v[154:157], v[186:189], v[74:77]
	v_mfma_f32_16x16x32_bf16 v[126:129], v[150:153], v[166:169], v[126:129]
	v_mfma_f32_16x16x32_bf16 v[122:125], v[158:161], v[166:169], v[122:125]
	v_mfma_f32_16x16x32_bf16 v[110:113], v[150:153], v[174:177], v[110:113]
	v_mfma_f32_16x16x32_bf16 v[106:109], v[158:161], v[174:177], v[106:109]
	v_mfma_f32_16x16x32_bf16 v[94:97], v[150:153], v[182:185], v[94:97]
	v_mfma_f32_16x16x32_bf16 v[90:93], v[158:161], v[182:185], v[90:93]
	v_mfma_f32_16x16x32_bf16 v[78:81], v[150:153], v[190:193], v[78:81]
	v_mfma_f32_16x16x32_bf16 v[74:77], v[158:161], v[190:193], v[74:77]
	s_barrier
	s_add_i32 s24, 0, 0x1c000
	s_add_i32 s25, s44, s30
	v_add_u32_e32 v206, s24, v143
	v_lshl_add_u64 v[140:141], v[140:141], 0, s[48:49]
	s_mov_b32 m0, s25
	ds_read_b128 v[194:197], v206
	ds_read_b128 v[198:201], v206 offset:1024
	ds_read_b128 v[202:205], v206 offset:2048
	ds_read_b128 v[206:209], v206 offset:3072
	global_load_lds_dwordx4 v[140:141], off
	v_lshl_add_u64 v[140:141], v[210:211], 0, s[48:49]
	s_add_i32 m0, s25, 0x2000
	s_nop 0
	global_load_lds_dwordx4 v[140:141], off
	s_barrier
	s_waitcnt lgkmcnt(0)
	v_mfma_f32_16x16x32_bf16 v[118:121], v[194:197], v[162:165], v[118:121]
	v_mfma_f32_16x16x32_bf16 v[114:117], v[202:205], v[162:165], v[114:117]
	v_mfma_f32_16x16x32_bf16 v[102:105], v[194:197], v[170:173], v[102:105]
	v_mfma_f32_16x16x32_bf16 v[98:101], v[202:205], v[170:173], v[98:101]
	v_mfma_f32_16x16x32_bf16 v[86:89], v[194:197], v[178:181], v[86:89]
	v_mfma_f32_16x16x32_bf16 v[82:85], v[202:205], v[178:181], v[82:85]
	v_mfma_f32_16x16x32_bf16 v[70:73], v[194:197], v[186:189], v[70:73]
	v_mfma_f32_16x16x32_bf16 v[66:69], v[202:205], v[186:189], v[66:69]
	v_mfma_f32_16x16x32_bf16 v[118:121], v[198:201], v[166:169], v[118:121]
	v_mfma_f32_16x16x32_bf16 v[114:117], v[206:209], v[166:169], v[114:117]
	v_mfma_f32_16x16x32_bf16 v[102:105], v[198:201], v[174:177], v[102:105]
	v_mfma_f32_16x16x32_bf16 v[98:101], v[206:209], v[174:177], v[98:101]
	v_mfma_f32_16x16x32_bf16 v[86:89], v[198:201], v[182:185], v[86:89]
	v_mfma_f32_16x16x32_bf16 v[82:85], v[206:209], v[182:185], v[82:85]
	v_mfma_f32_16x16x32_bf16 v[70:73], v[198:201], v[190:193], v[70:73]
	v_mfma_f32_16x16x32_bf16 v[66:69], v[206:209], v[190:193], v[66:69]
	s_mov_b32 m0, s37
	v_lshl_add_u64 v[140:141], v[220:221], 0, s[48:49]
	s_barrier
	ds_read_b128 v[162:165], v145 offset:49152
	ds_read_b128 v[166:169], v145 offset:50176
	ds_read_b128 v[170:173], v145 offset:51200
	ds_read_b128 v[174:177], v145 offset:52224
	ds_read_b128 v[178:181], v145 offset:53248
	ds_read_b128 v[182:185], v145 offset:54272
	ds_read_b128 v[186:189], v145 offset:55296
	ds_read_b128 v[190:193], v145 offset:56320
	global_load_lds_dwordx4 v[140:141], off
	v_lshl_add_u64 v[140:141], v[222:223], 0, s[48:49]
	s_mov_b32 m0, s38
	s_nop 0
	global_load_lds_dwordx4 v[140:141], off
	s_barrier
; __device__ __forceinline__ unsigned cvt_pk_bf16(float lo, float hi) { f32x2_t v = {lo, hi}; bf16x2_t b = __builtin_convertvector(v, bf16x2_t); return __builtin_bit_cast(unsigned, b); }
; #define PG8_STAGE(bufoff, gbase, voff) do { _Pragma("unroll") for (int _i = 0; _i < 2; ++_i) \
;         __builtin_amdgcn_global_load_lds((const unsigned*)((const char*)(gbase) + (voff)[_i]), (LAS unsigned*)(lds + (bufoff) + ldsw + _i * 8192), 16, 0, 0); } while (0)
; #define PG8_LDA(dst, b, h) do { _Pragma("unroll") for (int m = 0; m < 4; ++m) _Pragma("unroll") for (int k = 0; k < 2; ++k) dst[m][k] = *(const LAS bf16x8*)(lds + PG8_SA(b, h) + aoff + m * 2048 + k * 1024); } while (0)
; #define PG8_MMA(ai, bj, At, Bt) do { __builtin_amdgcn_s_setprio(1); _Pragma("unroll") for (int m = 0; m < 4; ++m) _Pragma("unroll") for (int n = 0; n < 2; ++n) _Pragma("unroll") for (int k = 0; k < 2; ++k) \
;         acc[ai][bj][m][n] = __builtin_amdgcn_mfma_f32_16x16x32_bf16(Bt[n][k], At[m][k], acc[ai][bj][m][n], 0, 0, 0); __builtin_amdgcn_s_setprio(0); } while (0)
; #define PG8_BAR __builtin_amdgcn_s_barrier()
; template <class Epi, class Sched>
; __device__ __forceinline__ void gemm_phase(LAS unsigned char* lds, const Gemm g, const Sched& S, const Epi& E) {
;     ...
;             PG8_LDA(At, 1, 1); PG8_STAGE(PG8_SA(1, 0), a3, voffA);
;             PG8_BAR; PG8_WAIT_L(0); PG8_MMA(1, 0, At, B0); PG8_BAR; PG8_SCHED;
;             PG8_STAGE(PG8_SB(1, 1), b3 + hstep, voffB);
;             PG8_WAIT_V(6); PG8_BAR; PG8_MMA(1, 1, At, B1); PG8_BAR;
;     __device__ __forceinline__ void operator()(const f32x4 (&acc)[2][2][4][2], const pg8::Unit& u, int wr, int wc, int fr, int fq) const {
;     ...
;                 for (int bj = 0; bj < 2; ++bj) { f32x4 v0 = acc[ai][bj][m][0], v1 = acc[ai][bj][m][1];
;                     if (ACT == 1) {
; #pragma unroll
;                         for (int j = 0; j < 4; ++j) { float a = fmaxf(v0[j], 0.f), b = fmaxf(v1[j], 0.f); v0[j] = a * a; v1[j] = b * b; } }
;                     if (ACT == 0) { if (u.pn == (C_G / 256) && bj == 0 && wc == 0 && fq < 2) { float* gp = gate + (size_t)row * 16 + 8 * fq; *(f32x4*)gp = v0; *(f32x4*)(gp + 4) = v1; } }
;                     u32x4 w; w.x = cvt_pk_bf16(v0[0], v0[1]); w.y = cvt_pk_bf16(v0[2], v0[3]); w.z = cvt_pk_bf16(v1[0], v1[1]); w.w = cvt_pk_bf16(v1[2], v1[3]);
;                     *(u32x4*)(rowp + bj * 128) = w; } }
	s_waitcnt lgkmcnt(0)
	v_mfma_f32_16x16x32_bf16 v[62:65], v[146:149], v[162:165], v[62:65]
	v_mfma_f32_16x16x32_bf16 v[58:61], v[154:157], v[162:165], v[58:61]
	v_mfma_f32_16x16x32_bf16 v[46:49], v[146:149], v[170:173], v[46:49]
	v_mfma_f32_16x16x32_bf16 v[42:45], v[154:157], v[170:173], v[42:45]
	v_mfma_f32_16x16x32_bf16 v[30:33], v[146:149], v[178:181], v[30:33]
	v_mfma_f32_16x16x32_bf16 v[26:29], v[154:157], v[178:181], v[26:29]
	v_mfma_f32_16x16x32_bf16 v[14:17], v[146:149], v[186:189], v[14:17]
	v_mfma_f32_16x16x32_bf16 v[10:13], v[154:157], v[186:189], v[10:13]
	v_mfma_f32_16x16x32_bf16 v[62:65], v[150:153], v[166:169], v[62:65]
	v_mfma_f32_16x16x32_bf16 v[58:61], v[158:161], v[166:169], v[58:61]
	v_mfma_f32_16x16x32_bf16 v[46:49], v[150:153], v[174:177], v[46:49]
	v_mfma_f32_16x16x32_bf16 v[42:45], v[158:161], v[174:177], v[42:45]
	v_mfma_f32_16x16x32_bf16 v[30:33], v[150:153], v[182:185], v[30:33]
	v_mfma_f32_16x16x32_bf16 v[26:29], v[158:161], v[182:185], v[26:29]
	v_mfma_f32_16x16x32_bf16 v[14:17], v[150:153], v[190:193], v[14:17]
	v_mfma_f32_16x16x32_bf16 v[10:13], v[158:161], v[190:193], v[10:13]
	s_barrier
	s_add_u32 s22, s22, 0x80080
	s_addc_u32 s23, s23, 0
	s_add_i32 s24, s24, s30
	s_mov_b32 m0, s24
	s_nop 0
	global_load_lds_dwordx4 v0, s[22:23]
	s_add_i32 m0, s24, 0x2000
	s_nop 0
	global_load_lds_dwordx4 v130, s[22:23]
	s_waitcnt vmcnt(6)
	s_barrier
	v_mfma_f32_16x16x32_bf16 v[54:57], v[194:197], v[162:165], v[54:57]
	v_mfma_f32_16x16x32_bf16 v[50:53], v[202:205], v[162:165], v[50:53]
	v_mfma_f32_16x16x32_bf16 v[38:41], v[194:197], v[170:173], v[38:41]
	v_mfma_f32_16x16x32_bf16 v[34:37], v[202:205], v[170:173], v[34:37]
	v_mfma_f32_16x16x32_bf16 v[22:25], v[194:197], v[178:181], v[22:25]
	v_mfma_f32_16x16x32_bf16 v[18:21], v[202:205], v[178:181], v[18:21]
	v_mfma_f32_16x16x32_bf16 v[6:9], v[194:197], v[186:189], v[6:9]
	v_mfma_f32_16x16x32_bf16 v[2:5], v[202:205], v[186:189], v[2:5]
	v_mfma_f32_16x16x32_bf16 v[54:57], v[198:201], v[166:169], v[54:57]
	v_mfma_f32_16x16x32_bf16 v[50:53], v[206:209], v[166:169], v[50:53]
	v_mfma_f32_16x16x32_bf16 v[38:41], v[198:201], v[174:177], v[38:41]
	v_mfma_f32_16x16x32_bf16 v[34:37], v[206:209], v[174:177], v[34:37]
	v_mfma_f32_16x16x32_bf16 v[22:25], v[198:201], v[182:185], v[22:25]
	v_mfma_f32_16x16x32_bf16 v[18:21], v[206:209], v[182:185], v[18:21]
	v_mfma_f32_16x16x32_bf16 v[6:9], v[198:201], v[190:193], v[6:9]
	v_mfma_f32_16x16x32_bf16 v[2:5], v[206:209], v[190:193], v[2:5]
	s_add_i32 s43, s43, 2
	s_add_u32 s20, s20, 0x100
	s_addc_u32 s21, s21, 0
	s_add_u32 s41, s41, 0x100
	s_addc_u32 s42, s42, 0
	s_cmp_gt_u32 s43, 29
	s_barrier
	s_cbranch_scc0 .LBB0_1279
	v_lshl_add_u32 v146, s18, 8, v142
	v_lshl_or_b32 v140, s16, 8, v144
	v_ashrrev_i32_e32 v147, 31, v146
	v_ashrrev_i32_e32 v141, 31, v140
	v_lshlrev_b64 v[148:149], 14, v[146:147]
	v_max_f32_e32 v122, v122, v122
	v_max_f32_e32 v123, v123, v123
	v_lshl_add_u64 v[148:149], s[58:59], 0, v[148:149]
	v_lshlrev_b64 v[150:151], 1, v[140:141]
	v_max_f32_e32 v122, 0, v122
	v_max_f32_e32 v123, 0, v123
	v_lshl_add_u64 v[140:141], v[148:149], 0, v[150:151]
	v_pk_mul_f32 v[148:149], v[122:123], v[122:123]
	v_max_f32_e32 v123, v124, v124
	v_max_f32_e32 v126, v126, v126
	v_max_f32_e32 v127, v127, v127
	v_max_f32_e32 v122, v128, v128
	v_max_f32_e32 v124, 0, v123
	v_max_f32_e32 v123, v129, v129
	v_max_f32_e32 v125, v125, v125
	v_max_f32_e32 v126, 0, v126
	v_max_f32_e32 v127, 0, v127
	v_max_f32_e32 v122, 0, v122
	v_max_f32_e32 v123, 0, v123
	v_max_f32_e32 v125, 0, v125
	v_pk_mul_f32 v[126:127], v[126:127], v[126:127]
	v_pk_mul_f32 v[128:129], v[122:123], v[122:123]
	v_pk_mul_f32 v[152:153], v[124:125], v[124:125]
	v_max_f32_e32 v114, v114, v114
	v_max_f32_e32 v115, v115, v115
	v_cvt_pk_bf16_f32 v122, v126, v127
	v_cvt_pk_bf16_f32 v123, v128, v129
	v_cvt_pk_bf16_f32 v124, v148, v149
	v_cvt_pk_bf16_f32 v125, v152, v153
	v_max_f32_e32 v114, 0, v114
	v_max_f32_e32 v115, 0, v115
	global_store_dwordx4 v[140:141], v[122:125], off
	v_max_f32_e32 v118, v118, v118
	v_max_f32_e32 v119, v119, v119
	v_pk_mul_f32 v[122:123], v[114:115], v[114:115]
	v_max_f32_e32 v115, v116, v116
	v_max_f32_e32 v114, v120, v120
	v_max_f32_e32 v116, 0, v115
	v_max_f32_e32 v115, v121, v121
	v_max_f32_e32 v117, v117, v117
	v_max_f32_e32 v118, 0, v118
	v_max_f32_e32 v119, 0, v119
	v_max_f32_e32 v114, 0, v114
	v_max_f32_e32 v115, 0, v115
	v_max_f32_e32 v117, 0, v117
	v_pk_mul_f32 v[118:119], v[118:119], v[118:119]
	v_pk_mul_f32 v[120:121], v[114:115], v[114:115]
	v_pk_mul_f32 v[124:125], v[116:117], v[116:117]
	v_max_f32_e32 v106, v106, v106
	v_max_f32_e32 v107, v107, v107
	v_cvt_pk_bf16_f32 v114, v118, v119
	v_cvt_pk_bf16_f32 v115, v120, v121
	v_cvt_pk_bf16_f32 v116, v122, v123
	v_cvt_pk_bf16_f32 v117, v124, v125
	v_max_f32_e32 v106, 0, v106
	v_max_f32_e32 v107, 0, v107
	global_store_dwordx4 v[140:141], v[114:117], off offset:256
	v_max_f32_e32 v110, v110, v110
	v_max_f32_e32 v111, v111, v111
	v_or_b32_e32 v114, 16, v146
	v_pk_mul_f32 v[116:117], v[106:107], v[106:107]
	v_max_f32_e32 v107, v108, v108
	v_ashrrev_i32_e32 v115, 31, v114
	v_max_f32_e32 v106, v112, v112
	v_max_f32_e32 v108, 0, v107
	v_max_f32_e32 v107, v113, v113
	v_max_f32_e32 v109, v109, v109
	v_lshlrev_b64 v[114:115], 14, v[114:115]
	v_max_f32_e32 v110, 0, v110
	v_max_f32_e32 v111, 0, v111
	v_max_f32_e32 v106, 0, v106
	v_max_f32_e32 v107, 0, v107
	v_max_f32_e32 v109, 0, v109
	v_lshl_add_u64 v[114:115], s[58:59], 0, v[114:115]
	v_pk_mul_f32 v[110:111], v[110:111], v[110:111]
	v_pk_mul_f32 v[112:113], v[106:107], v[106:107]
	v_pk_mul_f32 v[118:119], v[108:109], v[108:109]
	v_max_f32_e32 v98, v98, v98
	v_max_f32_e32 v99, v99, v99
; __device__ __forceinline__ unsigned cvt_pk_bf16(float lo, float hi) { f32x2_t v = {lo, hi}; bf16x2_t b = __builtin_convertvector(v, bf16x2_t); return __builtin_bit_cast(unsigned, b); }
;     __device__ __forceinline__ void operator()(const f32x4 (&acc)[2][2][4][2], const pg8::Unit& u, int wr, int wc, int fr, int fq) const {
;     ...
;             for (int m = 0; m < 4; ++m) { const int row = row0 + ai * 128 + m * 16; bf16_t* rowp = O + (size_t)row * ldc + col0;
; #pragma unroll
;                 for (int bj = 0; bj < 2; ++bj) { f32x4 v0 = acc[ai][bj][m][0], v1 = acc[ai][bj][m][1];
;                     if (ACT == 1) {
; #pragma unroll
;                         for (int j = 0; j < 4; ++j) { float a = fmaxf(v0[j], 0.f), b = fmaxf(v1[j], 0.f); v0[j] = a * a; v1[j] = b * b; } }
;                     if (ACT == 0) { if (u.pn == (C_G / 256) && bj == 0 && wc == 0 && fq < 2) { float* gp = gate + (size_t)row * 16 + 8 * fq; *(f32x4*)gp = v0; *(f32x4*)(gp + 4) = v1; } }
;                     u32x4 w; w.x = cvt_pk_bf16(v0[0], v0[1]); w.y = cvt_pk_bf16(v0[2], v0[3]); w.z = cvt_pk_bf16(v1[0], v1[1]); w.w = cvt_pk_bf16(v1[2], v1[3]);
;                     *(u32x4*)(rowp + bj * 128) = w; } }
	v_lshl_add_u64 v[114:115], v[114:115], 0, v[150:151]
	v_cvt_pk_bf16_f32 v106, v110, v111
	v_cvt_pk_bf16_f32 v107, v112, v113
	v_cvt_pk_bf16_f32 v108, v116, v117
	v_cvt_pk_bf16_f32 v109, v118, v119
	v_max_f32_e32 v98, 0, v98
	v_max_f32_e32 v99, 0, v99
	global_store_dwordx4 v[114:115], v[106:109], off
	v_max_f32_e32 v102, v102, v102
	v_max_f32_e32 v103, v103, v103
	v_pk_mul_f32 v[106:107], v[98:99], v[98:99]
	v_max_f32_e32 v99, v100, v100
	v_max_f32_e32 v98, v104, v104
	v_max_f32_e32 v100, 0, v99
	v_max_f32_e32 v99, v105, v105
	v_max_f32_e32 v101, v101, v101
	v_max_f32_e32 v102, 0, v102
	v_max_f32_e32 v103, 0, v103
	v_max_f32_e32 v98, 0, v98
	v_max_f32_e32 v99, 0, v99
	v_max_f32_e32 v101, 0, v101
	v_pk_mul_f32 v[102:103], v[102:103], v[102:103]
	v_pk_mul_f32 v[104:105], v[98:99], v[98:99]
	v_pk_mul_f32 v[108:109], v[100:101], v[100:101]
	v_max_f32_e32 v90, v90, v90
	v_max_f32_e32 v91, v91, v91
	v_cvt_pk_bf16_f32 v98, v102, v103
	v_cvt_pk_bf16_f32 v99, v104, v105
	v_cvt_pk_bf16_f32 v100, v106, v107
	v_cvt_pk_bf16_f32 v101, v108, v109
	v_max_f32_e32 v90, 0, v90
	v_max_f32_e32 v91, 0, v91
	global_store_dwordx4 v[114:115], v[98:101], off offset:256
	v_max_f32_e32 v94, v94, v94
	v_max_f32_e32 v95, v95, v95
	v_or_b32_e32 v98, 32, v146
	v_pk_mul_f32 v[100:101], v[90:91], v[90:91]
	v_max_f32_e32 v91, v92, v92
	v_ashrrev_i32_e32 v99, 31, v98
	v_max_f32_e32 v90, v96, v96
	v_max_f32_e32 v92, 0, v91
	v_max_f32_e32 v91, v97, v97
	v_max_f32_e32 v93, v93, v93
	v_lshlrev_b64 v[98:99], 14, v[98:99]
	v_max_f32_e32 v94, 0, v94
	v_max_f32_e32 v95, 0, v95
	v_max_f32_e32 v90, 0, v90
	v_max_f32_e32 v91, 0, v91
	v_max_f32_e32 v93, 0, v93
	v_lshl_add_u64 v[98:99], s[58:59], 0, v[98:99]
	v_pk_mul_f32 v[94:95], v[94:95], v[94:95]
	v_pk_mul_f32 v[96:97], v[90:91], v[90:91]
	v_pk_mul_f32 v[102:103], v[92:93], v[92:93]
	v_max_f32_e32 v82, v82, v82
	v_max_f32_e32 v83, v83, v83
	v_lshl_add_u64 v[98:99], v[98:99], 0, v[150:151]
	v_cvt_pk_bf16_f32 v90, v94, v95
	v_cvt_pk_bf16_f32 v91, v96, v97
	v_cvt_pk_bf16_f32 v92, v100, v101
	v_cvt_pk_bf16_f32 v93, v102, v103
	v_max_f32_e32 v82, 0, v82
	v_max_f32_e32 v83, 0, v83
	global_store_dwordx4 v[98:99], v[90:93], off
	v_max_f32_e32 v86, v86, v86
	v_max_f32_e32 v87, v87, v87
	v_pk_mul_f32 v[90:91], v[82:83], v[82:83]
	v_max_f32_e32 v83, v84, v84
	v_max_f32_e32 v82, v88, v88
	v_max_f32_e32 v84, 0, v83
	v_max_f32_e32 v83, v89, v89
	v_max_f32_e32 v85, v85, v85
	v_max_f32_e32 v86, 0, v86
	v_max_f32_e32 v87, 0, v87
	v_max_f32_e32 v82, 0, v82
	v_max_f32_e32 v83, 0, v83
	v_max_f32_e32 v85, 0, v85
	v_pk_mul_f32 v[86:87], v[86:87], v[86:87]
	v_pk_mul_f32 v[88:89], v[82:83], v[82:83]
	v_pk_mul_f32 v[92:93], v[84:85], v[84:85]
	v_max_f32_e32 v74, v74, v74
	v_max_f32_e32 v75, v75, v75
	v_cvt_pk_bf16_f32 v82, v86, v87
	v_cvt_pk_bf16_f32 v83, v88, v89
	v_cvt_pk_bf16_f32 v84, v90, v91
	v_cvt_pk_bf16_f32 v85, v92, v93
	v_max_f32_e32 v74, 0, v74
	v_max_f32_e32 v75, 0, v75
	global_store_dwordx4 v[98:99], v[82:85], off offset:256
	v_max_f32_e32 v78, v78, v78
	v_max_f32_e32 v79, v79, v79
	v_or_b32_e32 v82, 48, v146
	v_pk_mul_f32 v[84:85], v[74:75], v[74:75]
	v_max_f32_e32 v75, v76, v76
	v_ashrrev_i32_e32 v83, 31, v82
	v_max_f32_e32 v74, v80, v80
	v_max_f32_e32 v76, 0, v75
	v_max_f32_e32 v75, v81, v81
	v_max_f32_e32 v77, v77, v77
	v_lshlrev_b64 v[82:83], 14, v[82:83]
	v_max_f32_e32 v78, 0, v78
	v_max_f32_e32 v79, 0, v79
	v_max_f32_e32 v74, 0, v74
	v_max_f32_e32 v75, 0, v75
	v_max_f32_e32 v77, 0, v77
	v_lshl_add_u64 v[82:83], s[58:59], 0, v[82:83]
	v_pk_mul_f32 v[78:79], v[78:79], v[78:79]
	v_pk_mul_f32 v[80:81], v[74:75], v[74:75]
	v_pk_mul_f32 v[86:87], v[76:77], v[76:77]
	v_max_f32_e32 v66, v66, v66
	v_max_f32_e32 v67, v67, v67
	v_lshl_add_u64 v[82:83], v[82:83], 0, v[150:151]
	v_cvt_pk_bf16_f32 v74, v78, v79
	v_cvt_pk_bf16_f32 v75, v80, v81
	v_cvt_pk_bf16_f32 v76, v84, v85
	v_cvt_pk_bf16_f32 v77, v86, v87
	v_max_f32_e32 v66, 0, v66
	v_max_f32_e32 v67, 0, v67
	global_store_dwordx4 v[82:83], v[74:77], off
	v_max_f32_e32 v70, v70, v70
	v_max_f32_e32 v71, v71, v71
	v_pk_mul_f32 v[74:75], v[66:67], v[66:67]
	v_max_f32_e32 v67, v68, v68
	v_max_f32_e32 v66, v72, v72
	v_max_f32_e32 v68, 0, v67
	v_max_f32_e32 v67, v73, v73
	v_max_f32_e32 v69, v69, v69
	v_max_f32_e32 v70, 0, v70
	v_max_f32_e32 v71, 0, v71
	v_max_f32_e32 v66, 0, v66
	v_max_f32_e32 v67, 0, v67
	v_max_f32_e32 v69, 0, v69
	v_pk_mul_f32 v[70:71], v[70:71], v[70:71]
	v_pk_mul_f32 v[72:73], v[66:67], v[66:67]
	v_pk_mul_f32 v[76:77], v[68:69], v[68:69]
	v_max_f32_e32 v58, v58, v58
	v_max_f32_e32 v59, v59, v59
	v_cvt_pk_bf16_f32 v66, v70, v71
	v_cvt_pk_bf16_f32 v67, v72, v73
	v_cvt_pk_bf16_f32 v68, v74, v75
	v_cvt_pk_bf16_f32 v69, v76, v77
	v_max_f32_e32 v58, 0, v58
	v_max_f32_e32 v59, 0, v59
	global_store_dwordx4 v[82:83], v[66:69], off offset:256
	v_max_f32_e32 v62, v62, v62
	v_max_f32_e32 v63, v63, v63
	v_pk_mul_f32 v[68:69], v[58:59], v[58:59]
	v_max_f32_e32 v59, v60, v60
	v_max_f32_e32 v62, 0, v62
	v_max_f32_e32 v63, 0, v63
	v_max_f32_e32 v58, v64, v64
	v_max_f32_e32 v60, 0, v59
	v_max_f32_e32 v59, v65, v65
	v_max_f32_e32 v61, v61, v61
	v_pk_mul_f32 v[62:63], v[62:63], v[62:63]
	v_max_f32_e32 v58, 0, v58
	v_max_f32_e32 v59, 0, v59
	v_max_f32_e32 v61, 0, v61
	s_mov_b32 s3, 0x200000
	v_pk_mul_f32 v[64:65], v[58:59], v[58:59]
	v_pk_mul_f32 v[70:71], v[60:61], v[60:61]
	v_cvt_pk_bf16_f32 v58, v62, v63
	v_add_co_u32_e32 v62, vcc, s3, v140
	v_max_f32_e32 v50, v50, v50
	v_max_f32_e32 v51, v51, v51
	v_cvt_pk_bf16_f32 v59, v64, v65
	v_cvt_pk_bf16_f32 v60, v68, v69
	v_cvt_pk_bf16_f32 v61, v70, v71
	v_addc_co_u32_e32 v63, vcc, 0, v141, vcc
	v_max_f32_e32 v50, 0, v50
	v_max_f32_e32 v51, 0, v51
; __device__ __forceinline__ unsigned cvt_pk_bf16(float lo, float hi) { f32x2_t v = {lo, hi}; bf16x2_t b = __builtin_convertvector(v, bf16x2_t); return __builtin_bit_cast(unsigned, b); }
; #define PG8_WAIT_V(n) asm volatile("s_waitcnt vmcnt(" #n ")" ::: "memory")
; #define PG8_BAR __builtin_amdgcn_s_barrier()
; template <class Epi, class Sched>
; __device__ __forceinline__ void gemm_phase(LAS unsigned char* lds, const Gemm g, const Sched& S, const Epi& E) {
;     ...
;         E(acc, cur, wr, wc, fr, fq); S.done(cur);
;         if (!has_next) break;
; #pragma unroll
;         for (int a = 0; a < 2; ++a)
; #pragma unroll
;             for (int b = 0; b < 2; ++b)
; #pragma unroll
;                 for (int m = 0; m < 4; ++m)
; #pragma unroll
;                     for (int n = 0; n < 2; ++n) acc[a][b][m][n] = (f32x4){0.f, 0.f, 0.f, 0.f};
;         cur = nxt; cA = nA; cB = nB; ++ui;
;     }
;     PG8_WAIT_V(0);
;     if (wr == 0) PG8_BAR;
;     __device__ __forceinline__ void operator()(const f32x4 (&acc)[2][2][4][2], const pg8::Unit& u, int wr, int wc, int fr, int fq) const {
;     ...
;             for (int m = 0; m < 4; ++m) { const int row = row0 + ai * 128 + m * 16; bf16_t* rowp = O + (size_t)row * ldc + col0;
; #pragma unroll
;                 for (int bj = 0; bj < 2; ++bj) { f32x4 v0 = acc[ai][bj][m][0], v1 = acc[ai][bj][m][1];
;                     if (ACT == 1) {
; #pragma unroll
;                         for (int j = 0; j < 4; ++j) { float a = fmaxf(v0[j], 0.f), b = fmaxf(v1[j], 0.f); v0[j] = a * a; v1[j] = b * b; } }
;                     if (ACT == 0) { if (u.pn == (C_G / 256) && bj == 0 && wc == 0 && fq < 2) { float* gp = gate + (size_t)row * 16 + 8 * fq; *(f32x4*)gp = v0; *(f32x4*)(gp + 4) = v1; } }
;                     u32x4 w; w.x = cvt_pk_bf16(v0[0], v0[1]); w.y = cvt_pk_bf16(v0[2], v0[3]); w.z = cvt_pk_bf16(v1[0], v1[1]); w.w = cvt_pk_bf16(v1[2], v1[3]);
;                     *(u32x4*)(rowp + bj * 128) = w; } }
	global_store_dwordx4 v[62:63], v[58:61], off
	v_max_f32_e32 v54, v54, v54
	v_max_f32_e32 v55, v55, v55
	v_pk_mul_f32 v[58:59], v[50:51], v[50:51]
	v_max_f32_e32 v51, v52, v52
	v_max_f32_e32 v50, v56, v56
	v_max_f32_e32 v52, 0, v51
	v_max_f32_e32 v51, v57, v57
	v_max_f32_e32 v53, v53, v53
	v_max_f32_e32 v54, 0, v54
	v_max_f32_e32 v55, 0, v55
	v_max_f32_e32 v50, 0, v50
	v_max_f32_e32 v51, 0, v51
	v_max_f32_e32 v53, 0, v53
	s_mov_b64 s[20:21], 0x200000
	v_pk_mul_f32 v[54:55], v[54:55], v[54:55]
	v_pk_mul_f32 v[56:57], v[50:51], v[50:51]
	v_pk_mul_f32 v[60:61], v[52:53], v[52:53]
	v_max_f32_e32 v42, v42, v42
	v_max_f32_e32 v43, v43, v43
	v_lshl_add_u64 v[66:67], v[140:141], 0, s[20:21]
	v_cvt_pk_bf16_f32 v50, v54, v55
	v_cvt_pk_bf16_f32 v51, v56, v57
	v_cvt_pk_bf16_f32 v52, v58, v59
	v_cvt_pk_bf16_f32 v53, v60, v61
	v_max_f32_e32 v42, 0, v42
	v_max_f32_e32 v43, 0, v43
	global_store_dwordx4 v[66:67], v[50:53], off offset:256
	v_max_f32_e32 v46, v46, v46
	v_max_f32_e32 v47, v47, v47
	v_pk_mul_f32 v[52:53], v[42:43], v[42:43]
	v_max_f32_e32 v43, v44, v44
	v_max_f32_e32 v46, 0, v46
	v_max_f32_e32 v47, 0, v47
	v_max_f32_e32 v42, v48, v48
	v_max_f32_e32 v44, 0, v43
	v_max_f32_e32 v43, v49, v49
	v_max_f32_e32 v45, v45, v45
	v_pk_mul_f32 v[46:47], v[46:47], v[46:47]
	v_max_f32_e32 v42, 0, v42
	v_max_f32_e32 v43, 0, v43
	v_max_f32_e32 v45, 0, v45
	s_mov_b32 s3, 0x240000
	v_pk_mul_f32 v[48:49], v[42:43], v[42:43]
	v_pk_mul_f32 v[54:55], v[44:45], v[44:45]
	v_cvt_pk_bf16_f32 v42, v46, v47
	v_add_co_u32_e32 v46, vcc, s3, v140
	v_max_f32_e32 v34, v34, v34
	v_max_f32_e32 v35, v35, v35
	v_cvt_pk_bf16_f32 v43, v48, v49
	v_cvt_pk_bf16_f32 v44, v52, v53
	v_cvt_pk_bf16_f32 v45, v54, v55
	v_addc_co_u32_e32 v47, vcc, 0, v141, vcc
	v_max_f32_e32 v34, 0, v34
	v_max_f32_e32 v35, 0, v35
	global_store_dwordx4 v[46:47], v[42:45], off
	v_max_f32_e32 v38, v38, v38
	v_max_f32_e32 v39, v39, v39
	v_pk_mul_f32 v[42:43], v[34:35], v[34:35]
	v_max_f32_e32 v35, v36, v36
	v_max_f32_e32 v34, v40, v40
	v_max_f32_e32 v36, 0, v35
	v_max_f32_e32 v35, v41, v41
	v_max_f32_e32 v37, v37, v37
	v_max_f32_e32 v38, 0, v38
	v_max_f32_e32 v39, 0, v39
	v_max_f32_e32 v34, 0, v34
	v_max_f32_e32 v35, 0, v35
	v_max_f32_e32 v37, 0, v37
	s_mov_b64 s[20:21], 0x240000
	v_pk_mul_f32 v[38:39], v[38:39], v[38:39]
	v_pk_mul_f32 v[40:41], v[34:35], v[34:35]
	v_pk_mul_f32 v[44:45], v[36:37], v[36:37]
	v_max_f32_e32 v26, v26, v26
	v_max_f32_e32 v27, v27, v27
	v_lshl_add_u64 v[50:51], v[140:141], 0, s[20:21]
	v_cvt_pk_bf16_f32 v34, v38, v39
	v_cvt_pk_bf16_f32 v35, v40, v41
	v_cvt_pk_bf16_f32 v36, v42, v43
	v_cvt_pk_bf16_f32 v37, v44, v45
	v_max_f32_e32 v26, 0, v26
	v_max_f32_e32 v27, 0, v27
	global_store_dwordx4 v[50:51], v[34:37], off offset:256
	v_max_f32_e32 v30, v30, v30
	v_max_f32_e32 v31, v31, v31
	v_pk_mul_f32 v[36:37], v[26:27], v[26:27]
	v_max_f32_e32 v27, v28, v28
	v_max_f32_e32 v30, 0, v30
	v_max_f32_e32 v31, 0, v31
	v_max_f32_e32 v26, v32, v32
	v_max_f32_e32 v28, 0, v27
	v_max_f32_e32 v27, v33, v33
	v_max_f32_e32 v29, v29, v29
	v_pk_mul_f32 v[30:31], v[30:31], v[30:31]
	v_max_f32_e32 v26, 0, v26
	v_max_f32_e32 v27, 0, v27
	v_max_f32_e32 v29, 0, v29
	s_mov_b32 s3, 0x280000
	v_pk_mul_f32 v[32:33], v[26:27], v[26:27]
	v_pk_mul_f32 v[38:39], v[28:29], v[28:29]
	v_cvt_pk_bf16_f32 v26, v30, v31
	v_add_co_u32_e32 v30, vcc, s3, v140
	v_max_f32_e32 v18, v18, v18
	v_max_f32_e32 v19, v19, v19
	v_cvt_pk_bf16_f32 v27, v32, v33
	v_cvt_pk_bf16_f32 v28, v36, v37
	v_cvt_pk_bf16_f32 v29, v38, v39
	v_addc_co_u32_e32 v31, vcc, 0, v141, vcc
	v_max_f32_e32 v18, 0, v18
	v_max_f32_e32 v19, 0, v19
	global_store_dwordx4 v[30:31], v[26:29], off
	v_max_f32_e32 v22, v22, v22
	v_max_f32_e32 v23, v23, v23
	v_pk_mul_f32 v[26:27], v[18:19], v[18:19]
	v_max_f32_e32 v19, v20, v20
	v_max_f32_e32 v18, v24, v24
	v_max_f32_e32 v20, 0, v19
	v_max_f32_e32 v19, v25, v25
	v_max_f32_e32 v21, v21, v21
	v_max_f32_e32 v22, 0, v22
	v_max_f32_e32 v23, 0, v23
	v_max_f32_e32 v18, 0, v18
	v_max_f32_e32 v19, 0, v19
	v_max_f32_e32 v21, 0, v21
	s_mov_b64 s[20:21], 0x280000
	v_pk_mul_f32 v[22:23], v[22:23], v[22:23]
	v_pk_mul_f32 v[24:25], v[18:19], v[18:19]
	v_pk_mul_f32 v[28:29], v[20:21], v[20:21]
	v_max_f32_e32 v10, v10, v10
	v_max_f32_e32 v11, v11, v11
	v_lshl_add_u64 v[34:35], v[140:141], 0, s[20:21]
	v_cvt_pk_bf16_f32 v18, v22, v23
	v_cvt_pk_bf16_f32 v19, v24, v25
	v_cvt_pk_bf16_f32 v20, v26, v27
	v_cvt_pk_bf16_f32 v21, v28, v29
	v_max_f32_e32 v10, 0, v10
	v_max_f32_e32 v11, 0, v11
	global_store_dwordx4 v[34:35], v[18:21], off offset:256
	v_max_f32_e32 v14, v14, v14
	v_max_f32_e32 v15, v15, v15
	v_pk_mul_f32 v[20:21], v[10:11], v[10:11]
	v_max_f32_e32 v11, v12, v12
	v_max_f32_e32 v14, 0, v14
	v_max_f32_e32 v15, 0, v15
	v_max_f32_e32 v10, v16, v16
	v_max_f32_e32 v12, 0, v11
	v_max_f32_e32 v11, v17, v17
	v_max_f32_e32 v13, v13, v13
	v_pk_mul_f32 v[14:15], v[14:15], v[14:15]
	v_max_f32_e32 v10, 0, v10
	v_max_f32_e32 v11, 0, v11
	v_max_f32_e32 v13, 0, v13
	s_mov_b32 s3, 0x2c0000
	v_pk_mul_f32 v[16:17], v[10:11], v[10:11]
	v_pk_mul_f32 v[22:23], v[12:13], v[12:13]
	v_cvt_pk_bf16_f32 v10, v14, v15
	v_add_co_u32_e32 v14, vcc, s3, v140
	v_max_f32_e32 v2, v2, v2
	v_max_f32_e32 v3, v3, v3
	v_cvt_pk_bf16_f32 v11, v16, v17
	v_cvt_pk_bf16_f32 v12, v20, v21
	v_cvt_pk_bf16_f32 v13, v22, v23
	v_addc_co_u32_e32 v15, vcc, 0, v141, vcc
	v_max_f32_e32 v2, 0, v2
	v_max_f32_e32 v3, 0, v3
	global_store_dwordx4 v[14:15], v[10:13], off
	v_max_f32_e32 v6, v6, v6
	v_max_f32_e32 v7, v7, v7
	v_pk_mul_f32 v[10:11], v[2:3], v[2:3]
	v_max_f32_e32 v3, v4, v4
	v_max_f32_e32 v2, v8, v8
	v_max_f32_e32 v4, 0, v3
	v_max_f32_e32 v3, v9, v9
	v_max_f32_e32 v5, v5, v5
	v_max_f32_e32 v6, 0, v6
	v_max_f32_e32 v7, 0, v7
	v_max_f32_e32 v2, 0, v2
	v_max_f32_e32 v3, 0, v3
	v_max_f32_e32 v5, 0, v5
	s_mov_b64 s[20:21], 0x2c0000
	v_pk_mul_f32 v[6:7], v[6:7], v[6:7]
	v_pk_mul_f32 v[8:9], v[2:3], v[2:3]
	v_pk_mul_f32 v[12:13], v[4:5], v[4:5]
	v_lshl_add_u64 v[18:19], v[140:141], 0, s[20:21]
	v_cvt_pk_bf16_f32 v2, v6, v7
	v_cvt_pk_bf16_f32 v3, v8, v9
	v_cvt_pk_bf16_f32 v4, v10, v11
	v_cvt_pk_bf16_f32 v5, v12, v13
	s_and_b64 vcc, exec, s[0:1]
	s_mov_b32 s16, s8
	s_mov_b32 s18, s10
	s_mov_b64 s[22:23], s[14:15]
	s_mov_b64 s[20:21], s[12:13]
	global_store_dwordx4 v[18:19], v[2:5], off offset:256
	s_cbranch_vccz .LBB0_1276
	s_waitcnt vmcnt(0)
	s_cmpk_gt_u32 s27, 0xff
	s_cbranch_scc1 .LBB0_1283
	s_barrier
